# counted lgkmcnt(6/4/2/0) waits per MFMA in the attention PV sections (was one lgkmcnt(0) per group of 4)
# speedup vs baseline: 1.0063x; 1.0023x over previous
.LBB0_1096:
	ds_read_b128 v[64:67], v194 offset:49152
	ds_read_b128 v[68:71], v195 offset:57344
	ds_read_b128 v[214:217], v196 offset:49152
	ds_read_b128 v[224:227], v197 offset:57344
	v_add_f32_e32 v160, 0, v175
	v_add_f32_e32 v160, v223, v160
	s_waitcnt lgkmcnt(3)
	v_mfma_f32_32x32x16_bf16 v[80:95], v[64:67], v[100:103], 0
	v_add_f32_e32 v160, v161, v160
	v_add_f32_e32 v160, v220, v160
	v_add_f32_e32 v160, v162, v160
	v_add_f32_e32 v160, v174, v160
	v_add_f32_e32 v160, v163, v160
	v_add_f32_e32 v160, v173, v160
	v_add_f32_e32 v160, v164, v160
	s_waitcnt lgkmcnt(2)
	v_mfma_f32_32x32x16_bf16 v[64:79], v[68:71], v[100:103], 0
	v_add_f32_e32 v160, v172, v160
	v_add_f32_e32 v160, v165, v160
	v_add_f32_e32 v160, v171, v160
	v_exp_f32_e32 v156, v156
	v_add_f32_e32 v160, v166, v160
	v_exp_f32_e32 v157, v157
	v_add_f32_e32 v160, v170, v160
	s_waitcnt lgkmcnt(1)
	v_mfma_f32_32x32x16_bf16 v[80:95], v[214:217], v[108:111], v[80:95]
	v_exp_f32_e32 v154, v154
	v_add_f32_e32 v160, v167, v160
	v_exp_f32_e32 v155, v155
	v_add_f32_e32 v160, v169, v160
	v_exp_f32_e32 v148, v148
	v_add_f32_e32 v160, v156, v160
	v_exp_f32_e32 v149, v149
	s_waitcnt lgkmcnt(0)
	v_mfma_f32_32x32x16_bf16 v[64:79], v[224:227], v[108:111], v[64:79]
	ds_read_b128 v[214:217], v198 offset:49152
	ds_read_b128 v[224:227], v200 offset:57344
	v_add_f32_e32 v160, v157, v160
	v_exp_f32_e32 v146, v146
	v_add_f32_e32 v160, v154, v160
	v_exp_f32_e32 v147, v147
	v_add_f32_e32 v160, v155, v160
	v_exp_f32_e32 v144, v144
	s_waitcnt lgkmcnt(1)
	v_mfma_f32_32x32x16_bf16 v[80:95], v[214:217], v[96:99], v[80:95]
	v_add_f32_e32 v160, v148, v160
	v_exp_f32_e32 v145, v145
	v_add_f32_e32 v160, v149, v160
	v_exp_f32_e32 v158, v158
	v_add_f32_e32 v160, v146, v160
	v_exp_f32_e32 v159, v159
	v_add_f32_e32 v160, v147, v160
	s_waitcnt lgkmcnt(0)
	v_mfma_f32_32x32x16_bf16 v[64:79], v[224:227], v[96:99], v[64:79]
	ds_read_b128 v[214:217], v199 offset:49152
	ds_read_b128 v[224:227], v201 offset:57344
	v_exp_f32_e32 v152, v152
	v_add_f32_e32 v160, v144, v160
	v_exp_f32_e32 v153, v153
	v_add_f32_e32 v160, v145, v160
	v_exp_f32_e32 v150, v150
	v_add_f32_e32 v160, v158, v160
	s_waitcnt lgkmcnt(1)
	v_mfma_f32_32x32x16_bf16 v[80:95], v[214:217], v[104:107], v[80:95]
	v_exp_f32_e32 v151, v151
	v_add_f32_e32 v160, v159, v160
	v_add_f32_e32 v160, v152, v160
	v_add_f32_e32 v160, v153, v160
	v_add_f32_e32 v160, v150, v160
	v_add_f32_e32 v211, v151, v160
	v_mov_b32_e32 v218, v211
	s_waitcnt lgkmcnt(0)
	v_mfma_f32_32x32x16_bf16 v[64:79], v[224:227], v[104:107], v[64:79]
	ds_read_b128 v[214:217], v202 offset:49152
	ds_read_b128 v[224:227], v203 offset:57344
	v_permlane32_swap_b32_e32 v211, v218
	s_waitcnt lgkmcnt(1)
	v_mfma_f32_32x32x16_bf16 v[80:95], v[214:217], v[116:119], v[80:95]
	s_waitcnt lgkmcnt(0)
	v_mfma_f32_32x32x16_bf16 v[64:79], v[224:227], v[116:119], v[64:79]
	ds_read_b128 v[214:217], v204 offset:49152
	ds_read_b128 v[224:227], v205 offset:57344
	s_waitcnt lgkmcnt(1)
	v_mfma_f32_32x32x16_bf16 v[80:95], v[214:217], v[124:127], v[80:95]
	s_waitcnt lgkmcnt(0)
	v_mfma_f32_32x32x16_bf16 v[64:79], v[224:227], v[124:127], v[64:79]
	ds_read_b128 v[214:217], v206 offset:49152
	ds_read_b128 v[224:227], v208 offset:57344
	s_waitcnt lgkmcnt(1)
	v_mfma_f32_32x32x16_bf16 v[80:95], v[214:217], v[112:115], v[80:95]
	s_waitcnt lgkmcnt(0)
	v_mfma_f32_32x32x16_bf16 v[64:79], v[224:227], v[112:115], v[64:79]
	ds_read_b128 v[214:217], v207 offset:49152
	ds_read_b128 v[224:227], v209 offset:57344
	v_cvt_pk_bf16_f32 v160, v175, v223
	v_cvt_pk_bf16_f32 v161, v161, v220
	v_cvt_pk_bf16_f32 v162, v162, v174
	v_cvt_pk_bf16_f32 v163, v163, v173
	v_cvt_pk_bf16_f32 v164, v164, v172
	v_cvt_pk_bf16_f32 v165, v165, v171
	s_waitcnt lgkmcnt(1)
	v_mfma_f32_32x32x16_bf16 v[80:95], v[214:217], v[120:123], v[80:95]
	v_permlane32_swap_b32_e32 v160, v162
	v_cvt_pk_bf16_f32 v166, v166, v170
	v_cvt_pk_bf16_f32 v167, v167, v169
	v_cvt_pk_bf16_f32 v170, v156, v157
	v_cvt_pk_bf16_f32 v171, v154, v155
	v_cvt_pk_bf16_f32 v172, v148, v149
	s_waitcnt lgkmcnt(0)
	v_mfma_f32_32x32x16_bf16 v[64:79], v[224:227], v[120:123], v[64:79]
	v_cvt_pk_bf16_f32 v173, v146, v147
	v_cvt_pk_bf16_f32 v214, v144, v145
	v_cvt_pk_bf16_f32 v215, v158, v159
	v_cvt_pk_bf16_f32 v216, v152, v153
	v_cvt_pk_bf16_f32 v217, v150, v151
	v_permlane32_swap_b32_e32 v161, v163
	v_permlane32_swap_b32_e32 v164, v166
	v_permlane32_swap_b32_e32 v165, v167
	v_permlane32_swap_b32_e32 v170, v172
	v_permlane32_swap_b32_e32 v171, v173
	v_permlane32_swap_b32_e32 v214, v216
	v_permlane32_swap_b32_e32 v215, v217
	v_lshl_add_u64 v[144:145], v[180:181], 0, s[8:9]
	s_mov_b32 s2, 0x322f0000
	v_add_co_u32_e32 v146, vcc, s2, v144
	s_mov_b32 s2, 0x32318000
	s_nop 0
	v_addc_co_u32_e32 v147, vcc, 0, v145, vcc
	v_add_co_u32_e32 v148, vcc, s2, v144
	v_lshl_add_u64 v[152:153], v[178:179], 0, s[8:9]
	s_nop 0
	v_addc_co_u32_e32 v149, vcc, 0, v145, vcc
	s_mov_b32 s2, 0x41018000
	v_add_co_u32_e32 v154, vcc, s2, v152
	s_mov_b32 s2, 0x4101c000
	s_nop 0
	v_addc_co_u32_e32 v155, vcc, 0, v153, vcc
	v_add_co_u32_e32 v156, vcc, s2, v152
	global_load_dwordx4 v[144:147], v[146:147], off offset:2560
	s_nop 0
	global_load_dwordx4 v[148:151], v[148:149], off offset:2560
	v_addc_co_u32_e32 v157, vcc, 0, v153, vcc
	global_load_dwordx4 v[152:155], v[154:155], off
	s_nop 0
	global_load_dwordx4 v[156:159], v[156:157], off
	ds_read_b64_tr_b16 v[220:221], v189 offset:0
	ds_read_b64_tr_b16 v[222:223], v189 offset:0x800
	ds_read_b64_tr_b16 v[224:225], v189 offset:0x1000
	ds_read_b64_tr_b16 v[226:227], v189 offset:0x1800
	ds_read_b64_tr_b16 v[230:231], v189 offset:0x2000
	ds_read_b64_tr_b16 v[232:233], v189 offset:0x2800
	ds_read_b64_tr_b16 v[238:239], v189 offset:0x3000
	ds_read_b64_tr_b16 v[240:241], v189 offset:0x3800
	s_waitcnt lgkmcnt(6)
	s_nop 0
	v_mfma_f32_32x32x16_bf16 v[0:15], v[160:163], v[220:223], v[0:15]
	ds_read_b64_tr_b16 v[220:221], v189 offset:0x200
	ds_read_b64_tr_b16 v[222:223], v189 offset:0xa00
	s_waitcnt lgkmcnt(6)
	v_mfma_f32_32x32x16_bf16 v[0:15], v[164:167], v[224:227], v[0:15]
	ds_read_b64_tr_b16 v[224:225], v189 offset:0x1200
	ds_read_b64_tr_b16 v[226:227], v189 offset:0x1a00
	s_waitcnt lgkmcnt(6)
	v_mfma_f32_32x32x16_bf16 v[0:15], v[170:173], v[230:233], v[0:15]
	ds_read_b64_tr_b16 v[230:231], v189 offset:0x2200
	ds_read_b64_tr_b16 v[232:233], v189 offset:0x2a00
	s_waitcnt lgkmcnt(6)
	v_mfma_f32_32x32x16_bf16 v[0:15], v[214:217], v[238:241], v[0:15]
	ds_read_b64_tr_b16 v[238:239], v189 offset:0x3200
	ds_read_b64_tr_b16 v[240:241], v189 offset:0x3a00
	s_waitcnt lgkmcnt(6)
	v_mfma_f32_32x32x16_bf16 v[48:63], v[160:163], v[220:223], v[48:63]
	ds_read_b64_tr_b16 v[220:221], v189 offset:0x400
	ds_read_b64_tr_b16 v[222:223], v189 offset:0xc00
	s_waitcnt lgkmcnt(6)
	v_mfma_f32_32x32x16_bf16 v[48:63], v[164:167], v[224:227], v[48:63]
	ds_read_b64_tr_b16 v[224:225], v189 offset:0x1400
	ds_read_b64_tr_b16 v[226:227], v189 offset:0x1c00
	s_waitcnt lgkmcnt(6)
	v_mfma_f32_32x32x16_bf16 v[48:63], v[170:173], v[230:233], v[48:63]
	ds_read_b64_tr_b16 v[230:231], v189 offset:0x2400
	ds_read_b64_tr_b16 v[232:233], v189 offset:0x2c00
	s_waitcnt lgkmcnt(6)
	v_mfma_f32_32x32x16_bf16 v[48:63], v[214:217], v[238:241], v[48:63]
	ds_read_b64_tr_b16 v[238:239], v189 offset:0x3400
	ds_read_b64_tr_b16 v[240:241], v189 offset:0x3c00
	s_waitcnt lgkmcnt(6)
	v_mfma_f32_32x32x16_bf16 v[32:47], v[160:163], v[220:223], v[32:47]
	ds_read_b64_tr_b16 v[220:221], v189 offset:0x600
	ds_read_b64_tr_b16 v[222:223], v189 offset:0xe00
	s_waitcnt lgkmcnt(6)
	v_mfma_f32_32x32x16_bf16 v[32:47], v[164:167], v[224:227], v[32:47]
	ds_read_b64_tr_b16 v[224:225], v189 offset:0x1600
	ds_read_b64_tr_b16 v[226:227], v189 offset:0x1e00
	s_waitcnt lgkmcnt(6)
	v_mfma_f32_32x32x16_bf16 v[32:47], v[170:173], v[230:233], v[32:47]
	ds_read_b64_tr_b16 v[230:231], v189 offset:0x2600
	ds_read_b64_tr_b16 v[232:233], v189 offset:0x2e00
	s_waitcnt lgkmcnt(6)
	v_mfma_f32_32x32x16_bf16 v[32:47], v[214:217], v[238:241], v[32:47]
	ds_read_b64_tr_b16 v[238:239], v189 offset:0x3600
	ds_read_b64_tr_b16 v[240:241], v189 offset:0x3e00
	s_waitcnt lgkmcnt(6)
	v_mfma_f32_32x32x16_bf16 v[16:31], v[160:163], v[220:223], v[16:31]
	v_max_f32_e32 v160, v81, v81
	v_max_f32_e32 v161, v80, v80
	v_max_f32_e32 v160, v161, v160
	v_max3_f32 v160, v160, v82, v83
	v_max3_f32 v160, v160, v84, v85
	v_max3_f32 v160, v160, v86, v87
	v_max3_f32 v160, v160, v88, v89
	v_max3_f32 v160, v160, v90, v91
	v_max3_f32 v160, v160, v92, v93
	s_waitcnt lgkmcnt(4)
	v_mfma_f32_32x32x16_bf16 v[16:31], v[164:167], v[224:227], v[16:31]
	v_max3_f32 v160, v160, v94, v95
	v_max3_f32 v160, v160, v64, v65
	v_max3_f32 v160, v160, v66, v67
	v_max3_f32 v160, v160, v68, v69
	v_max3_f32 v160, v160, v70, v71
	v_max3_f32 v160, v160, v72, v73
	v_max3_f32 v160, v160, v74, v75
	v_max3_f32 v160, v160, v76, v77
	s_waitcnt lgkmcnt(2)
	v_mfma_f32_32x32x16_bf16 v[16:31], v[170:173], v[230:233], v[16:31]
	v_max3_f32 v160, v160, v78, v79
	v_mov_b32_e32 v161, v160
	s_nop 1
	v_permlane32_swap_b32_e32 v160, v161
	v_max_f32_e32 v161, v161, v161
	v_max_f32_e32 v160, v160, v160
	v_max_f32_e32 v160, v160, v161
	v_sub_f32_e32 v161, v160, v168
	v_cmp_ge_f32_e32 vcc, s90, v161
	v_max_f32_e32 v161, v168, v168
	v_max_f32_e32 v160, v161, v160
	s_waitcnt lgkmcnt(0)
	v_mfma_f32_32x32x16_bf16 v[16:31], v[214:217], v[238:241], v[16:31]
	v_sub_f32_e32 v161, v168, v160
	v_mul_f32_e32 v161, 0x3e0293ee, v161
	v_exp_f32_e32 v161, v161
	s_cmp_eq_u64 vcc, exec
	s_cselect_b64 s[38:39], -1, 0
	s_barrier
	s_waitcnt vmcnt(4)
	v_cndmask_b32_e64 v219, v161, 1.0, s[38:39]
	v_cmp_gt_f32_e32 vcc, 1.0, v219
	s_waitcnt vmcnt(7)
	ds_write_b128 v190, v[128:131]
	s_waitcnt vmcnt(6)
	ds_write_b128 v191, v[132:135]
	s_waitcnt vmcnt(5)
	ds_write_b128 v192, v[136:139] offset:32768
	s_waitcnt vmcnt(4)
	ds_write_b128 v193, v[140:143] offset:32768
	s_cbranch_vccz .LBB0_1100
	s_and_saveexec_b64 s[2:3], s[36:37]
	ds_write_b32 v186, v219 offset:128
	s_or_b64 exec, exec, s[2:3]
	s_waitcnt lgkmcnt(0)
	v_add_u32_e32 v161, s27, v185
	ds_read_b128 v[162:165], v161 offset:224
	ds_read_b128 v[170:173], v161 offset:192
	ds_read_b128 v[214:217], v161 offset:160
	ds_read_b128 v[220:223], v161 offset:128
	s_waitcnt lgkmcnt(3)
	v_pk_mul_f32 v[12:13], v[12:13], v[162:163]
	s_waitcnt lgkmcnt(2)
	v_pk_mul_f32 v[8:9], v[8:9], v[170:171]
	s_waitcnt lgkmcnt(1)
	v_pk_mul_f32 v[4:5], v[4:5], v[214:215]
	v_pk_mul_f32 v[14:15], v[14:15], v[164:165]
	v_pk_mul_f32 v[10:11], v[10:11], v[172:173]
	v_pk_mul_f32 v[6:7], v[6:7], v[216:217]
	s_waitcnt lgkmcnt(0)
	v_pk_mul_f32 v[2:3], v[2:3], v[222:223]
	v_pk_mul_f32 v[0:1], v[0:1], v[220:221]
	v_pk_mul_f32 v[60:61], v[60:61], v[162:163]
	v_pk_mul_f32 v[56:57], v[56:57], v[170:171]
	v_pk_mul_f32 v[52:53], v[52:53], v[214:215]
	v_pk_mul_f32 v[62:63], v[62:63], v[164:165]
	v_pk_mul_f32 v[58:59], v[58:59], v[172:173]
	v_pk_mul_f32 v[54:55], v[54:55], v[216:217]
	v_pk_mul_f32 v[50:51], v[50:51], v[222:223]
	v_pk_mul_f32 v[48:49], v[48:49], v[220:221]
	v_pk_mul_f32 v[44:45], v[44:45], v[162:163]
	v_pk_mul_f32 v[40:41], v[40:41], v[170:171]
	v_pk_mul_f32 v[36:37], v[36:37], v[214:215]
	v_pk_mul_f32 v[46:47], v[46:47], v[164:165]
	v_pk_mul_f32 v[42:43], v[42:43], v[172:173]
	v_pk_mul_f32 v[38:39], v[38:39], v[216:217]
	v_pk_mul_f32 v[34:35], v[34:35], v[222:223]
	v_pk_mul_f32 v[32:33], v[32:33], v[220:221]
	v_pk_mul_f32 v[28:29], v[28:29], v[162:163]
	v_pk_mul_f32 v[24:25], v[24:25], v[170:171]
	v_pk_mul_f32 v[20:21], v[20:21], v[214:215]
	v_pk_mul_f32 v[30:31], v[30:31], v[164:165]
	v_pk_mul_f32 v[26:27], v[26:27], v[172:173]
	v_pk_mul_f32 v[22:23], v[22:23], v[216:217]
	v_pk_mul_f32 v[18:19], v[18:19], v[222:223]
	v_pk_mul_f32 v[16:17], v[16:17], v[220:221]

.LBB0_1102:
	ds_read_b64_tr_b16 v[214:215], v188 offset:0
	ds_read_b64_tr_b16 v[216:217], v188 offset:0x800
	ds_read_b64_tr_b16 v[224:225], v188 offset:0x1000
	ds_read_b64_tr_b16 v[226:227], v188 offset:0x1800
	ds_read_b64_tr_b16 v[230:231], v188 offset:0x2000
	ds_read_b64_tr_b16 v[232:233], v188 offset:0x2800
	ds_read_b64_tr_b16 v[238:239], v188 offset:0x3000
	ds_read_b64_tr_b16 v[240:241], v188 offset:0x3800
	s_waitcnt lgkmcnt(6)
	s_nop 0
	v_mfma_f32_32x32x16_bf16 v[0:15], v[160:163], v[214:217], v[0:15]
	ds_read_b64_tr_b16 v[214:215], v188 offset:0x200
	ds_read_b64_tr_b16 v[216:217], v188 offset:0xa00
	s_waitcnt lgkmcnt(6)
	v_mfma_f32_32x32x16_bf16 v[0:15], v[164:167], v[224:227], v[0:15]
	ds_read_b64_tr_b16 v[224:225], v188 offset:0x1200
	ds_read_b64_tr_b16 v[226:227], v188 offset:0x1a00
	s_waitcnt lgkmcnt(6)
	v_mfma_f32_32x32x16_bf16 v[0:15], v[168:171], v[230:233], v[0:15]
	ds_read_b64_tr_b16 v[230:231], v188 offset:0x2200
	ds_read_b64_tr_b16 v[232:233], v188 offset:0x2a00
	s_waitcnt lgkmcnt(6)
	v_mfma_f32_32x32x16_bf16 v[0:15], v[172:175], v[238:241], v[0:15]
	ds_read_b64_tr_b16 v[238:239], v188 offset:0x3200
	ds_read_b64_tr_b16 v[240:241], v188 offset:0x3a00
	s_waitcnt lgkmcnt(6)
	v_mfma_f32_32x32x16_bf16 v[48:63], v[160:163], v[214:217], v[48:63]
	ds_read_b64_tr_b16 v[214:215], v188 offset:0x400
	ds_read_b64_tr_b16 v[216:217], v188 offset:0xc00
	s_waitcnt lgkmcnt(6)
	v_mfma_f32_32x32x16_bf16 v[48:63], v[164:167], v[224:227], v[48:63]
	ds_read_b64_tr_b16 v[224:225], v188 offset:0x1400
	ds_read_b64_tr_b16 v[226:227], v188 offset:0x1c00
	s_waitcnt lgkmcnt(6)
	v_mfma_f32_32x32x16_bf16 v[48:63], v[168:171], v[230:233], v[48:63]
	ds_read_b64_tr_b16 v[230:231], v188 offset:0x2400
	ds_read_b64_tr_b16 v[232:233], v188 offset:0x2c00
	s_waitcnt lgkmcnt(6)
	v_mfma_f32_32x32x16_bf16 v[48:63], v[172:175], v[238:241], v[48:63]
	ds_read_b64_tr_b16 v[238:239], v188 offset:0x3400
	ds_read_b64_tr_b16 v[240:241], v188 offset:0x3c00
	s_waitcnt lgkmcnt(6)
	v_mfma_f32_32x32x16_bf16 v[32:47], v[160:163], v[214:217], v[32:47]
	ds_read_b64_tr_b16 v[214:215], v188 offset:0x600
	ds_read_b64_tr_b16 v[216:217], v188 offset:0xe00
	s_waitcnt lgkmcnt(6)
	v_mfma_f32_32x32x16_bf16 v[32:47], v[164:167], v[224:227], v[32:47]
	ds_read_b64_tr_b16 v[224:225], v188 offset:0x1600
	ds_read_b64_tr_b16 v[226:227], v188 offset:0x1e00
	s_waitcnt lgkmcnt(6)
	v_mfma_f32_32x32x16_bf16 v[32:47], v[168:171], v[230:233], v[32:47]
	ds_read_b64_tr_b16 v[230:231], v188 offset:0x2600
	ds_read_b64_tr_b16 v[232:233], v188 offset:0x2e00
	s_waitcnt lgkmcnt(6)
	v_mfma_f32_32x32x16_bf16 v[32:47], v[172:175], v[238:241], v[32:47]
	ds_read_b64_tr_b16 v[238:239], v188 offset:0x3600
	ds_read_b64_tr_b16 v[240:241], v188 offset:0x3e00
	s_waitcnt lgkmcnt(6)
	v_mfma_f32_32x32x16_bf16 v[16:31], v[160:163], v[214:217], v[16:31]
	v_max_f32_e32 v160, v81, v81
	v_max_f32_e32 v161, v80, v80
	v_max_f32_e32 v160, v161, v160
	v_max3_f32 v160, v160, v82, v83
	v_max3_f32 v160, v160, v84, v85
	v_max3_f32 v160, v160, v86, v87
	v_max3_f32 v160, v160, v88, v89
	v_max3_f32 v160, v160, v90, v91
	v_max3_f32 v160, v160, v92, v93
	s_waitcnt lgkmcnt(4)
	v_mfma_f32_32x32x16_bf16 v[16:31], v[164:167], v[224:227], v[16:31]
	v_max3_f32 v160, v160, v94, v95
	v_max3_f32 v160, v160, v64, v65
	v_max3_f32 v160, v160, v66, v67
	v_max3_f32 v160, v160, v68, v69
	v_max3_f32 v160, v160, v70, v71
	v_max3_f32 v160, v160, v72, v73
	v_max3_f32 v160, v160, v74, v75
	v_max3_f32 v160, v160, v76, v77
	s_waitcnt lgkmcnt(2)
	v_mfma_f32_32x32x16_bf16 v[16:31], v[168:171], v[230:233], v[16:31]
	v_max3_f32 v160, v160, v78, v79
	v_mov_b32_e32 v161, v160
	s_nop 1
	v_permlane32_swap_b32_e32 v160, v161
	v_max_f32_e32 v161, v161, v161
	v_max_f32_e32 v160, v160, v160
	v_max_f32_e32 v160, v160, v161
	v_sub_f32_e32 v161, v160, v220
	v_cmp_ge_f32_e32 vcc, s90, v161
	v_max_f32_e32 v161, v220, v220
	v_max_f32_e32 v161, v161, v160
	s_waitcnt lgkmcnt(0)
	v_mfma_f32_32x32x16_bf16 v[16:31], v[172:175], v[238:241], v[16:31]
	v_sub_f32_e32 v160, v220, v161
	v_mul_f32_e32 v160, 0x3e0293ee, v160
	v_exp_f32_e32 v160, v160
	s_cmp_eq_u64 vcc, exec
	s_cselect_b64 s[38:39], -1, 0
	s_barrier
	s_waitcnt vmcnt(4)
	v_cndmask_b32_e64 v160, v160, 1.0, s[38:39]
	v_cmp_gt_f32_e32 vcc, 1.0, v160
	s_waitcnt vmcnt(3)
	ds_write_b128 v190, v[144:147] offset:16384
	s_waitcnt vmcnt(2)
	ds_write_b128 v191, v[148:151] offset:16384
	s_waitcnt vmcnt(1)
	ds_write_b128 v192, v[152:155] offset:49152
	s_waitcnt vmcnt(0)
	ds_write_b128 v193, v[156:159] offset:49152
	s_cbranch_vccz .LBB0_1106
	s_and_saveexec_b64 s[2:3], s[36:37]
	ds_write_b32 v186, v160 offset:128
	s_or_b64 exec, exec, s[2:3]
	s_waitcnt lgkmcnt(0)
	v_add_u32_e32 v156, s27, v185
	ds_read_b128 v[144:147], v156 offset:224
	ds_read_b128 v[148:151], v156 offset:192
	ds_read_b128 v[152:155], v156 offset:160
	ds_read_b128 v[156:159], v156 offset:128
	s_waitcnt lgkmcnt(3)
	v_pk_mul_f32 v[12:13], v[12:13], v[144:145]
	s_waitcnt lgkmcnt(2)
	v_pk_mul_f32 v[8:9], v[8:9], v[148:149]
	s_waitcnt lgkmcnt(1)
	v_pk_mul_f32 v[4:5], v[4:5], v[152:153]
	v_pk_mul_f32 v[14:15], v[14:15], v[146:147]
	v_pk_mul_f32 v[10:11], v[10:11], v[150:151]
	v_pk_mul_f32 v[6:7], v[6:7], v[154:155]
	s_waitcnt lgkmcnt(0)
	v_pk_mul_f32 v[2:3], v[2:3], v[158:159]
	v_pk_mul_f32 v[0:1], v[0:1], v[156:157]
	v_pk_mul_f32 v[60:61], v[60:61], v[144:145]
	v_pk_mul_f32 v[56:57], v[56:57], v[148:149]
	v_pk_mul_f32 v[52:53], v[52:53], v[152:153]
	v_pk_mul_f32 v[62:63], v[62:63], v[146:147]
	v_pk_mul_f32 v[58:59], v[58:59], v[150:151]
	v_pk_mul_f32 v[54:55], v[54:55], v[154:155]
	v_pk_mul_f32 v[50:51], v[50:51], v[158:159]
	v_pk_mul_f32 v[48:49], v[48:49], v[156:157]
	v_pk_mul_f32 v[44:45], v[44:45], v[144:145]
	v_pk_mul_f32 v[40:41], v[40:41], v[148:149]
	v_pk_mul_f32 v[36:37], v[36:37], v[152:153]
	v_pk_mul_f32 v[46:47], v[46:47], v[146:147]
	v_pk_mul_f32 v[42:43], v[42:43], v[150:151]
	v_pk_mul_f32 v[38:39], v[38:39], v[154:155]
	v_pk_mul_f32 v[34:35], v[34:35], v[158:159]
	v_pk_mul_f32 v[32:33], v[32:33], v[156:157]
	v_pk_mul_f32 v[28:29], v[28:29], v[144:145]
	v_pk_mul_f32 v[24:25], v[24:25], v[148:149]
	v_pk_mul_f32 v[20:21], v[20:21], v[152:153]
	v_pk_mul_f32 v[30:31], v[30:31], v[146:147]
	v_pk_mul_f32 v[26:27], v[26:27], v[150:151]
	v_pk_mul_f32 v[22:23], v[22:23], v[154:155]
	v_pk_mul_f32 v[18:19], v[18:19], v[158:159]
	v_pk_mul_f32 v[16:17], v[16:17], v[156:157]

.LBB0_1108:
	ds_read_b128 v[64:67], v194 offset:49152
	ds_read_b128 v[68:71], v195 offset:57344
	s_waitcnt lgkmcnt(1)
	v_mfma_f32_32x32x16_bf16 v[80:95], v[64:67], v[100:103], 0
	s_waitcnt lgkmcnt(0)
	v_mfma_f32_32x32x16_bf16 v[64:79], v[68:71], v[100:103], 0
	ds_read_b128 v[100:103], v196 offset:49152
	ds_read_b128 v[128:131], v197 offset:57344
	s_waitcnt lgkmcnt(1)
	v_mfma_f32_32x32x16_bf16 v[80:95], v[100:103], v[108:111], v[80:95]
	s_waitcnt lgkmcnt(0)
	v_mfma_f32_32x32x16_bf16 v[64:79], v[128:131], v[108:111], v[64:79]
	ds_read_b128 v[100:103], v198 offset:49152
	ds_read_b128 v[108:111], v200 offset:57344
	s_waitcnt lgkmcnt(1)
	v_mfma_f32_32x32x16_bf16 v[80:95], v[100:103], v[96:99], v[80:95]
	s_waitcnt lgkmcnt(0)
	v_mfma_f32_32x32x16_bf16 v[64:79], v[108:111], v[96:99], v[64:79]
	ds_read_b128 v[96:99], v199 offset:49152
	ds_read_b128 v[100:103], v201 offset:57344
	v_exp_f32_e32 v108, v154
	v_exp_f32_e32 v109, v155
	v_exp_f32_e32 v110, v148
	v_exp_f32_e32 v111, v149
	s_waitcnt lgkmcnt(1)
	v_mfma_f32_32x32x16_bf16 v[80:95], v[96:99], v[104:107], v[80:95]
	s_waitcnt lgkmcnt(0)
	v_mfma_f32_32x32x16_bf16 v[64:79], v[100:103], v[104:107], v[64:79]
	ds_read_b128 v[96:99], v202 offset:49152
	ds_read_b128 v[100:103], v203 offset:57344
	v_exp_f32_e32 v106, v156
	v_exp_f32_e32 v107, v157
	s_waitcnt lgkmcnt(1)
	v_mfma_f32_32x32x16_bf16 v[80:95], v[96:99], v[116:119], v[80:95]
	s_waitcnt lgkmcnt(0)
	v_mfma_f32_32x32x16_bf16 v[64:79], v[100:103], v[116:119], v[64:79]
	ds_read_b128 v[96:99], v204 offset:49152
	ds_read_b128 v[100:103], v205 offset:57344
	v_exp_f32_e32 v116, v158
	v_exp_f32_e32 v117, v159
	v_exp_f32_e32 v118, v152
	v_exp_f32_e32 v119, v153
	s_waitcnt lgkmcnt(1)
	v_mfma_f32_32x32x16_bf16 v[80:95], v[96:99], v[124:127], v[80:95]
	s_waitcnt lgkmcnt(0)
	v_mfma_f32_32x32x16_bf16 v[64:79], v[100:103], v[124:127], v[64:79]
	ds_read_b128 v[96:99], v206 offset:49152
	ds_read_b128 v[100:103], v208 offset:57344
	s_waitcnt lgkmcnt(1)
	v_mfma_f32_32x32x16_bf16 v[80:95], v[96:99], v[112:115], v[80:95]
	s_waitcnt lgkmcnt(0)
	v_mfma_f32_32x32x16_bf16 v[64:79], v[100:103], v[112:115], v[64:79]
	ds_read_b128 v[96:99], v207 offset:49152
	ds_read_b128 v[100:103], v209 offset:57344
	v_exp_f32_e32 v112, v146
	v_exp_f32_e32 v113, v147
	v_exp_f32_e32 v114, v144
	v_exp_f32_e32 v115, v145
	s_waitcnt lgkmcnt(1)
	v_mfma_f32_32x32x16_bf16 v[80:95], v[96:99], v[120:123], v[80:95]
	v_add_f32_e32 v96, 0, v175
	v_add_f32_e32 v96, v223, v96
	v_add_f32_e32 v96, v161, v96
	v_add_f32_e32 v96, v220, v96
	v_add_f32_e32 v96, v162, v96
	v_add_f32_e32 v96, v174, v96
	v_add_f32_e32 v96, v163, v96
	v_add_f32_e32 v96, v173, v96
	v_add_f32_e32 v96, v164, v96
	v_add_f32_e32 v96, v172, v96
	v_add_f32_e32 v96, v165, v96
	v_add_f32_e32 v96, v171, v96
	v_add_f32_e32 v96, v166, v96
	v_add_f32_e32 v96, v170, v96
	v_add_f32_e32 v96, v167, v96
	v_add_f32_e32 v96, v169, v96
	v_add_f32_e32 v96, v106, v96
	v_add_f32_e32 v96, v107, v96
	v_add_f32_e32 v96, v108, v96
	v_add_f32_e32 v96, v109, v96
	v_add_f32_e32 v96, v110, v96
	v_add_f32_e32 v96, v111, v96
	v_add_f32_e32 v96, v112, v96
	v_add_f32_e32 v96, v113, v96
	v_add_f32_e32 v96, v114, v96
	v_add_f32_e32 v96, v115, v96
	s_waitcnt lgkmcnt(0)
	v_mfma_f32_32x32x16_bf16 v[64:79], v[100:103], v[120:123], v[64:79]
	v_exp_f32_e32 v120, v150
	v_add_f32_e32 v96, v116, v96
	v_exp_f32_e32 v121, v151
	v_add_f32_e32 v96, v117, v96
	v_add_f32_e32 v96, v118, v96
	v_add_f32_e32 v96, v119, v96
	v_add_f32_e32 v96, v120, v96
	v_add_f32_e32 v96, v121, v96
	v_mov_b32_e32 v97, v96
	v_cvt_pk_bf16_f32 v98, v175, v223
	v_cvt_pk_bf16_f32 v99, v161, v220
	v_cvt_pk_bf16_f32 v100, v162, v174
	v_cvt_pk_bf16_f32 v101, v163, v173
	s_nop 1
	v_permlane32_swap_b32_e32 v96, v97
	v_permlane32_swap_b32_e32 v98, v100
	v_permlane32_swap_b32_e32 v99, v101
	v_cvt_pk_bf16_f32 v102, v164, v172
	v_cvt_pk_bf16_f32 v103, v165, v171
	v_cvt_pk_bf16_f32 v104, v166, v170
	v_cvt_pk_bf16_f32 v105, v167, v169
	v_cvt_pk_bf16_f32 v106, v106, v107
	v_cvt_pk_bf16_f32 v107, v108, v109
	v_cvt_pk_bf16_f32 v108, v110, v111
	v_cvt_pk_bf16_f32 v109, v112, v113
	v_cvt_pk_bf16_f32 v110, v114, v115
	v_cvt_pk_bf16_f32 v111, v116, v117
	v_cvt_pk_bf16_f32 v112, v118, v119
	v_cvt_pk_bf16_f32 v113, v120, v121
	s_nop 0
	v_permlane32_swap_b32_e32 v102, v104
	v_permlane32_swap_b32_e32 v103, v105
	v_permlane32_swap_b32_e32 v106, v108
	v_permlane32_swap_b32_e32 v107, v109
	v_permlane32_swap_b32_e32 v110, v112
	v_permlane32_swap_b32_e32 v111, v113
	ds_read_b64_tr_b16 v[114:115], v189 offset:0
	ds_read_b64_tr_b16 v[116:117], v189 offset:0x800
	ds_read_b64_tr_b16 v[118:119], v189 offset:0x1000
	ds_read_b64_tr_b16 v[120:121], v189 offset:0x1800
	ds_read_b64_tr_b16 v[122:123], v189 offset:0x2000
	ds_read_b64_tr_b16 v[124:125], v189 offset:0x2800
	ds_read_b64_tr_b16 v[126:127], v189 offset:0x3000
	ds_read_b64_tr_b16 v[128:129], v189 offset:0x3800
	s_waitcnt lgkmcnt(6)
	s_nop 0
	v_mfma_f32_32x32x16_bf16 v[0:15], v[98:101], v[114:117], v[0:15]
	ds_read_b64_tr_b16 v[114:115], v189 offset:0x200
	ds_read_b64_tr_b16 v[116:117], v189 offset:0xa00
	s_waitcnt lgkmcnt(6)
	v_mfma_f32_32x32x16_bf16 v[0:15], v[102:105], v[118:121], v[0:15]
	ds_read_b64_tr_b16 v[118:119], v189 offset:0x1200
	ds_read_b64_tr_b16 v[120:121], v189 offset:0x1a00
	s_waitcnt lgkmcnt(6)
	v_mfma_f32_32x32x16_bf16 v[0:15], v[106:109], v[122:125], v[0:15]
	ds_read_b64_tr_b16 v[122:123], v189 offset:0x2200
	ds_read_b64_tr_b16 v[124:125], v189 offset:0x2a00
	s_waitcnt lgkmcnt(6)
	v_mfma_f32_32x32x16_bf16 v[0:15], v[110:113], v[126:129], v[0:15]
	ds_read_b64_tr_b16 v[126:127], v189 offset:0x3200
	ds_read_b64_tr_b16 v[128:129], v189 offset:0x3a00
	s_waitcnt lgkmcnt(6)
	v_mfma_f32_32x32x16_bf16 v[48:63], v[98:101], v[114:117], v[48:63]
	ds_read_b64_tr_b16 v[114:115], v189 offset:0x400
	ds_read_b64_tr_b16 v[116:117], v189 offset:0xc00
	s_waitcnt lgkmcnt(6)
	v_mfma_f32_32x32x16_bf16 v[48:63], v[102:105], v[118:121], v[48:63]
	ds_read_b64_tr_b16 v[118:119], v189 offset:0x1400
	ds_read_b64_tr_b16 v[120:121], v189 offset:0x1c00
	s_waitcnt lgkmcnt(6)
	v_mfma_f32_32x32x16_bf16 v[48:63], v[106:109], v[122:125], v[48:63]
	ds_read_b64_tr_b16 v[122:123], v189 offset:0x2400
	ds_read_b64_tr_b16 v[124:125], v189 offset:0x2c00
	s_waitcnt lgkmcnt(6)
	v_mfma_f32_32x32x16_bf16 v[48:63], v[110:113], v[126:129], v[48:63]
	ds_read_b64_tr_b16 v[126:127], v189 offset:0x3400
	ds_read_b64_tr_b16 v[128:129], v189 offset:0x3c00
	s_waitcnt lgkmcnt(6)
	v_mfma_f32_32x32x16_bf16 v[32:47], v[98:101], v[114:117], v[32:47]
	ds_read_b64_tr_b16 v[114:115], v189 offset:0x600
	ds_read_b64_tr_b16 v[116:117], v189 offset:0xe00
	s_waitcnt lgkmcnt(6)
	v_mfma_f32_32x32x16_bf16 v[32:47], v[102:105], v[118:121], v[32:47]
	ds_read_b64_tr_b16 v[118:119], v189 offset:0x1600
	ds_read_b64_tr_b16 v[120:121], v189 offset:0x1e00
	s_waitcnt lgkmcnt(6)
	v_mfma_f32_32x32x16_bf16 v[32:47], v[106:109], v[122:125], v[32:47]
	ds_read_b64_tr_b16 v[122:123], v189 offset:0x2600
	ds_read_b64_tr_b16 v[124:125], v189 offset:0x2e00
	s_waitcnt lgkmcnt(6)
	v_mfma_f32_32x32x16_bf16 v[32:47], v[110:113], v[126:129], v[32:47]
	ds_read_b64_tr_b16 v[126:127], v189 offset:0x3600
	ds_read_b64_tr_b16 v[128:129], v189 offset:0x3e00
	s_waitcnt lgkmcnt(6)
	v_mfma_f32_32x32x16_bf16 v[16:31], v[98:101], v[114:117], v[16:31]
	v_max_f32_e32 v98, v81, v81
	v_max_f32_e32 v99, v80, v80
	v_max_f32_e32 v98, v99, v98
	v_max3_f32 v98, v98, v82, v83
	v_max3_f32 v98, v98, v84, v85
	v_max3_f32 v98, v98, v86, v87
	v_max3_f32 v98, v98, v88, v89
	v_max3_f32 v98, v98, v90, v91
	v_max3_f32 v98, v98, v92, v93
	s_waitcnt lgkmcnt(4)
	v_mfma_f32_32x32x16_bf16 v[16:31], v[102:105], v[118:121], v[16:31]
	v_max3_f32 v98, v98, v94, v95
	v_max3_f32 v98, v98, v64, v65
	v_max3_f32 v98, v98, v66, v67
	v_max3_f32 v98, v98, v68, v69
	v_max3_f32 v98, v98, v70, v71
	v_max3_f32 v98, v98, v72, v73
	v_max3_f32 v98, v98, v74, v75
	v_max3_f32 v98, v98, v76, v77
	s_waitcnt lgkmcnt(2)
	v_mfma_f32_32x32x16_bf16 v[16:31], v[106:109], v[122:125], v[16:31]
	v_max3_f32 v98, v98, v78, v79
	v_mov_b32_e32 v99, v98
	s_nop 1
	v_permlane32_swap_b32_e32 v98, v99
	v_max_f32_e32 v99, v99, v99
	v_max_f32_e32 v98, v98, v98
	v_max_f32_e32 v98, v98, v99
	v_sub_f32_e32 v99, v98, v168
	v_cmp_ge_f32_e32 vcc, s90, v99
	v_max_f32_e32 v99, v168, v168
	v_max_f32_e32 v99, v99, v98
	s_waitcnt lgkmcnt(0)
	v_mfma_f32_32x32x16_bf16 v[16:31], v[110:113], v[126:129], v[16:31]
	v_sub_f32_e32 v98, v168, v99
	v_mul_f32_e32 v98, 0x3e0293ee, v98
	v_exp_f32_e32 v98, v98
	s_cmp_eq_u64 vcc, exec
	s_cselect_b64 s[38:39], -1, 0
	v_cndmask_b32_e64 v98, v98, 1.0, s[38:39]
	v_cmp_gt_f32_e32 vcc, 1.0, v98
	s_barrier
	s_cbranch_vccz .LBB0_1112
	s_and_saveexec_b64 s[2:3], s[36:37]
	ds_write_b32 v186, v98 offset:128
	s_or_b64 exec, exec, s[2:3]
	s_waitcnt lgkmcnt(0)
	v_add_u32_e32 v112, s27, v185
	ds_read_b128 v[100:103], v112 offset:224
	ds_read_b128 v[104:107], v112 offset:192
	ds_read_b128 v[108:111], v112 offset:160
	ds_read_b128 v[112:115], v112 offset:128
	s_waitcnt lgkmcnt(3)
	v_pk_mul_f32 v[12:13], v[12:13], v[100:101]
	s_waitcnt lgkmcnt(2)
	v_pk_mul_f32 v[8:9], v[8:9], v[104:105]
	s_waitcnt lgkmcnt(1)
	v_pk_mul_f32 v[4:5], v[4:5], v[108:109]
	v_pk_mul_f32 v[14:15], v[14:15], v[102:103]
	v_pk_mul_f32 v[10:11], v[10:11], v[106:107]
	v_pk_mul_f32 v[6:7], v[6:7], v[110:111]
	s_waitcnt lgkmcnt(0)
	v_pk_mul_f32 v[2:3], v[2:3], v[114:115]
	v_pk_mul_f32 v[0:1], v[0:1], v[112:113]
	v_pk_mul_f32 v[60:61], v[60:61], v[100:101]
	v_pk_mul_f32 v[56:57], v[56:57], v[104:105]
	v_pk_mul_f32 v[52:53], v[52:53], v[108:109]
	v_pk_mul_f32 v[62:63], v[62:63], v[102:103]
	v_pk_mul_f32 v[58:59], v[58:59], v[106:107]
	v_pk_mul_f32 v[54:55], v[54:55], v[110:111]
	v_pk_mul_f32 v[50:51], v[50:51], v[114:115]
	v_pk_mul_f32 v[48:49], v[48:49], v[112:113]
	v_pk_mul_f32 v[44:45], v[44:45], v[100:101]
	v_pk_mul_f32 v[40:41], v[40:41], v[104:105]
	v_pk_mul_f32 v[36:37], v[36:37], v[108:109]
	v_pk_mul_f32 v[46:47], v[46:47], v[102:103]
	v_pk_mul_f32 v[42:43], v[42:43], v[106:107]
	v_pk_mul_f32 v[38:39], v[38:39], v[110:111]
	v_pk_mul_f32 v[34:35], v[34:35], v[114:115]
	v_pk_mul_f32 v[32:33], v[32:33], v[112:113]
	v_pk_mul_f32 v[28:29], v[28:29], v[100:101]
	v_pk_mul_f32 v[24:25], v[24:25], v[104:105]
	v_pk_mul_f32 v[20:21], v[20:21], v[108:109]
	v_pk_mul_f32 v[30:31], v[30:31], v[102:103]
	v_pk_mul_f32 v[26:27], v[26:27], v[106:107]
	v_pk_mul_f32 v[22:23], v[22:23], v[110:111]
	v_pk_mul_f32 v[18:19], v[18:19], v[114:115]
	v_pk_mul_f32 v[16:17], v[16:17], v[112:113]

.LBB0_1135:
	ds_read_b128 v[64:67], v194 offset:57344
	ds_read_b128 v[68:71], v212 offset:57344
	ds_read_b128 v[214:217], v197 offset:57344
	ds_read_b128 v[230:233], v211 offset:57344
	v_add_f32_e32 v164, 0, v165
	v_add_f32_e32 v164, v224, v164
	s_waitcnt lgkmcnt(3)
	v_mfma_f32_32x32x16_bf16 v[80:95], v[64:67], v[140:143], 0
	v_add_f32_e32 v164, v166, v164
	v_add_f32_e32 v164, v225, v164
	v_add_f32_e32 v164, v223, v164
	v_add_f32_e32 v164, v226, v164
	v_add_f32_e32 v164, v167, v164
	v_add_f32_e32 v164, v222, v164
	v_add_f32_e32 v164, v172, v164
	s_waitcnt lgkmcnt(2)
	v_mfma_f32_32x32x16_bf16 v[64:79], v[68:71], v[140:143], 0
	v_add_f32_e32 v164, v174, v164
	v_add_f32_e32 v164, v173, v164
	v_add_f32_e32 v164, v175, v164
	v_exp_f32_e32 v158, v158
	v_add_f32_e32 v164, v160, v164
	v_exp_f32_e32 v159, v159
	v_add_f32_e32 v164, v162, v164
	s_waitcnt lgkmcnt(1)
	v_mfma_f32_32x32x16_bf16 v[80:95], v[214:217], v[136:139], v[80:95]
	v_exp_f32_e32 v156, v156
	v_add_f32_e32 v164, v161, v164
	v_exp_f32_e32 v157, v157
	v_add_f32_e32 v164, v163, v164
	v_exp_f32_e32 v152, v152
	v_add_f32_e32 v164, v158, v164
	v_exp_f32_e32 v153, v153
	s_waitcnt lgkmcnt(0)
	v_mfma_f32_32x32x16_bf16 v[64:79], v[230:233], v[136:139], v[64:79]
	ds_read_b128 v[214:217], v196 offset:57344
	ds_read_b128 v[230:233], v210 offset:57344
	v_add_f32_e32 v164, v159, v164
	v_exp_f32_e32 v148, v148
	v_add_f32_e32 v164, v156, v164
	v_exp_f32_e32 v149, v149
	v_add_f32_e32 v164, v157, v164
	v_exp_f32_e32 v146, v146
	s_waitcnt lgkmcnt(1)
	v_mfma_f32_32x32x16_bf16 v[80:95], v[214:217], v[132:135], v[80:95]
	v_add_f32_e32 v164, v152, v164
	v_exp_f32_e32 v147, v147
	v_add_f32_e32 v164, v153, v164
	v_exp_f32_e32 v154, v154
	v_add_f32_e32 v164, v148, v164
	v_exp_f32_e32 v155, v155
	v_add_f32_e32 v164, v149, v164
	s_waitcnt lgkmcnt(0)
	v_mfma_f32_32x32x16_bf16 v[64:79], v[230:233], v[132:135], v[64:79]
	ds_read_b128 v[214:217], v195 offset:57344
	ds_read_b128 v[230:233], v209 offset:57344
	v_exp_f32_e32 v150, v150
	v_add_f32_e32 v164, v146, v164
	v_exp_f32_e32 v151, v151
	v_add_f32_e32 v164, v147, v164
	v_exp_f32_e32 v144, v144
	v_add_f32_e32 v164, v154, v164
	s_waitcnt lgkmcnt(1)
	v_mfma_f32_32x32x16_bf16 v[80:95], v[214:217], v[128:131], v[80:95]
	v_exp_f32_e32 v145, v145
	v_add_f32_e32 v164, v155, v164
	v_add_f32_e32 v164, v150, v164
	v_add_f32_e32 v164, v151, v164
	v_add_f32_e32 v164, v144, v164
	v_add_f32_e32 v219, v145, v164
	v_mov_b32_e32 v220, v219
	s_waitcnt lgkmcnt(0)
	v_mfma_f32_32x32x16_bf16 v[64:79], v[230:233], v[128:131], v[64:79]
	ds_read_b128 v[214:217], v193 offset:57344
	ds_read_b128 v[230:233], v208 offset:57344
	v_permlane32_swap_b32_e32 v219, v220
	s_waitcnt lgkmcnt(1)
	v_mfma_f32_32x32x16_bf16 v[80:95], v[214:217], v[124:127], v[80:95]
	s_waitcnt lgkmcnt(0)
	v_mfma_f32_32x32x16_bf16 v[64:79], v[230:233], v[124:127], v[64:79]
	ds_read_b128 v[214:217], v192 offset:57344
	ds_read_b128 v[230:233], v206 offset:57344
	s_waitcnt lgkmcnt(1)
	v_mfma_f32_32x32x16_bf16 v[80:95], v[214:217], v[120:123], v[80:95]
	s_waitcnt lgkmcnt(0)
	v_mfma_f32_32x32x16_bf16 v[64:79], v[230:233], v[120:123], v[64:79]
	ds_read_b128 v[214:217], v186 offset:57344
	ds_read_b128 v[230:233], v205 offset:57344
	s_waitcnt lgkmcnt(1)
	v_mfma_f32_32x32x16_bf16 v[80:95], v[214:217], v[116:119], v[80:95]
	s_waitcnt lgkmcnt(0)
	v_mfma_f32_32x32x16_bf16 v[64:79], v[230:233], v[116:119], v[64:79]
	ds_read_b128 v[214:217], v189 offset:57344
	ds_read_b128 v[230:233], v204 offset:57344
	s_waitcnt lgkmcnt(1)
	v_mfma_f32_32x32x16_bf16 v[80:95], v[214:217], v[112:115], v[80:95]
	s_waitcnt lgkmcnt(0)
	v_mfma_f32_32x32x16_bf16 v[64:79], v[230:233], v[112:115], v[64:79]
	ds_read_b128 v[214:217], v190 offset:57344
	ds_read_b128 v[230:233], v203 offset:57344
	s_waitcnt lgkmcnt(1)
	v_mfma_f32_32x32x16_bf16 v[80:95], v[214:217], v[108:111], v[80:95]
	s_waitcnt lgkmcnt(0)
	v_mfma_f32_32x32x16_bf16 v[64:79], v[230:233], v[108:111], v[64:79]
	ds_read_b128 v[214:217], v188 offset:57344
	ds_read_b128 v[230:233], v202 offset:57344
	s_waitcnt lgkmcnt(1)
	v_mfma_f32_32x32x16_bf16 v[80:95], v[214:217], v[104:107], v[80:95]
	s_waitcnt lgkmcnt(0)
	v_mfma_f32_32x32x16_bf16 v[64:79], v[230:233], v[104:107], v[64:79]
	ds_read_b128 v[214:217], v199 offset:57344
	ds_read_b128 v[230:233], v201 offset:57344
	s_waitcnt lgkmcnt(1)
	v_mfma_f32_32x32x16_bf16 v[80:95], v[214:217], v[100:103], v[80:95]
	s_waitcnt lgkmcnt(0)
	v_mfma_f32_32x32x16_bf16 v[64:79], v[230:233], v[100:103], v[64:79]
	ds_read_b128 v[214:217], v198 offset:57344
	ds_read_b128 v[230:233], v200 offset:57344
	v_cvt_pk_bf16_f32 v164, v165, v224
	v_cvt_pk_bf16_f32 v165, v166, v225
	v_cvt_pk_bf16_f32 v166, v223, v226
	v_cvt_pk_bf16_f32 v167, v167, v222
	s_nop 0
	v_permlane32_swap_b32_e32 v164, v166
	s_waitcnt lgkmcnt(1)
	v_mfma_f32_32x32x16_bf16 v[80:95], v[214:217], v[96:99], v[80:95]
	v_cvt_pk_bf16_f32 v214, v172, v174
	v_cvt_pk_bf16_f32 v215, v173, v175
	v_cvt_pk_bf16_f32 v216, v160, v162
	v_cvt_pk_bf16_f32 v217, v161, v163
	v_cvt_pk_bf16_f32 v222, v158, v159
	v_cvt_pk_bf16_f32 v223, v156, v157
	v_cvt_pk_bf16_f32 v224, v152, v153
	s_waitcnt lgkmcnt(0)
	v_mfma_f32_32x32x16_bf16 v[64:79], v[230:233], v[96:99], v[64:79]
	v_cvt_pk_bf16_f32 v225, v148, v149
	v_cvt_pk_bf16_f32 v230, v146, v147
	v_cvt_pk_bf16_f32 v231, v154, v155
	v_cvt_pk_bf16_f32 v232, v150, v151
	v_cvt_pk_bf16_f32 v233, v144, v145
	v_permlane32_swap_b32_e32 v165, v167
	v_permlane32_swap_b32_e32 v214, v216
	v_permlane32_swap_b32_e32 v215, v217
	v_permlane32_swap_b32_e32 v222, v224
	v_permlane32_swap_b32_e32 v223, v225
	v_permlane32_swap_b32_e32 v230, v232
	v_permlane32_swap_b32_e32 v231, v233
	v_lshl_add_u64 v[172:173], s[44:45], 0, v[170:171]
	s_mov_b32 s2, 0x4bf80000
	v_add_co_u32_e32 v148, vcc, s2, v172
	s_mov_b32 s2, 0x4bfa0000
	s_nop 0
	v_addc_co_u32_e32 v149, vcc, 0, v173, vcc
	v_add_co_u32_e32 v152, vcc, s2, v172
	v_lshl_add_u64 v[174:175], s[44:45], 0, v[168:169]
	s_nop 0
	v_addc_co_u32_e32 v153, vcc, 0, v173, vcc
	global_load_dwordx4 v[144:147], v[148:149], off offset:256
	s_nop 0
	global_load_dwordx4 v[148:151], v[148:149], off
	s_nop 0
	global_load_dwordx4 v[156:159], v[152:153], off offset:256
	s_nop 0
	global_load_dwordx4 v[152:155], v[152:153], off
	s_mov_b32 s2, 0x45404000
	v_add_co_u32_e32 v160, vcc, s2, v174
	s_nop 1
	v_addc_co_u32_e32 v161, vcc, 0, v175, vcc
	global_load_dwordx4 v[160:163], v[160:161], off
	ds_read_b64_tr_b16 v[238:239], v182 offset:0
	ds_read_b64_tr_b16 v[240:241], v182 offset:0x800
	ds_read_b64_tr_b16 v[242:243], v182 offset:0x1000
	ds_read_b64_tr_b16 v[244:245], v182 offset:0x1800
	ds_read_b64_tr_b16 v[246:247], v182 offset:0x2000
	ds_read_b64_tr_b16 v[248:249], v182 offset:0x2800
	ds_read_b64_tr_b16 v[250:251], v182 offset:0x3000
	ds_read_b64_tr_b16 v[252:253], v182 offset:0x3800
	s_waitcnt lgkmcnt(6)
	s_nop 0
	v_mfma_f32_32x32x16_bf16 v[0:15], v[164:167], v[238:241], v[0:15]
	ds_read_b64_tr_b16 v[238:239], v182 offset:0x200
	ds_read_b64_tr_b16 v[240:241], v182 offset:0xa00
	s_waitcnt lgkmcnt(6)
	v_mfma_f32_32x32x16_bf16 v[0:15], v[214:217], v[242:245], v[0:15]
	ds_read_b64_tr_b16 v[242:243], v182 offset:0x1200
	ds_read_b64_tr_b16 v[244:245], v182 offset:0x1a00
	s_waitcnt lgkmcnt(6)
	v_mfma_f32_32x32x16_bf16 v[0:15], v[222:225], v[246:249], v[0:15]
	ds_read_b64_tr_b16 v[246:247], v182 offset:0x2200
	ds_read_b64_tr_b16 v[248:249], v182 offset:0x2a00
	s_waitcnt lgkmcnt(6)
	v_mfma_f32_32x32x16_bf16 v[0:15], v[230:233], v[250:253], v[0:15]
	ds_read_b64_tr_b16 v[250:251], v182 offset:0x3200
	ds_read_b64_tr_b16 v[252:253], v182 offset:0x3a00
	s_waitcnt lgkmcnt(6)
	v_mfma_f32_32x32x16_bf16 v[48:63], v[164:167], v[238:241], v[48:63]
	ds_read_b64_tr_b16 v[238:239], v182 offset:0x400
	ds_read_b64_tr_b16 v[240:241], v182 offset:0xc00
	s_waitcnt lgkmcnt(6)
	v_mfma_f32_32x32x16_bf16 v[48:63], v[214:217], v[242:245], v[48:63]
	ds_read_b64_tr_b16 v[242:243], v182 offset:0x1400
	ds_read_b64_tr_b16 v[244:245], v182 offset:0x1c00
	s_waitcnt lgkmcnt(6)
	v_mfma_f32_32x32x16_bf16 v[48:63], v[222:225], v[246:249], v[48:63]
	ds_read_b64_tr_b16 v[246:247], v182 offset:0x2400
	ds_read_b64_tr_b16 v[248:249], v182 offset:0x2c00
	s_waitcnt lgkmcnt(6)
	v_mfma_f32_32x32x16_bf16 v[48:63], v[230:233], v[250:253], v[48:63]
	ds_read_b64_tr_b16 v[250:251], v182 offset:0x3400
	ds_read_b64_tr_b16 v[252:253], v182 offset:0x3c00
	s_waitcnt lgkmcnt(6)
	v_mfma_f32_32x32x16_bf16 v[32:47], v[164:167], v[238:241], v[32:47]
	ds_read_b64_tr_b16 v[238:239], v182 offset:0x600
	ds_read_b64_tr_b16 v[240:241], v182 offset:0xe00
	s_waitcnt lgkmcnt(6)
	v_mfma_f32_32x32x16_bf16 v[32:47], v[214:217], v[242:245], v[32:47]
	ds_read_b64_tr_b16 v[242:243], v182 offset:0x1600
	ds_read_b64_tr_b16 v[244:245], v182 offset:0x1e00
	s_waitcnt lgkmcnt(6)
	v_mfma_f32_32x32x16_bf16 v[32:47], v[222:225], v[246:249], v[32:47]
	ds_read_b64_tr_b16 v[246:247], v182 offset:0x2600
	ds_read_b64_tr_b16 v[248:249], v182 offset:0x2e00
	s_waitcnt lgkmcnt(6)
	v_mfma_f32_32x32x16_bf16 v[32:47], v[230:233], v[250:253], v[32:47]
	ds_read_b64_tr_b16 v[250:251], v182 offset:0x3600
	ds_read_b64_tr_b16 v[252:253], v182 offset:0x3e00
	s_waitcnt lgkmcnt(6)
	v_mfma_f32_32x32x16_bf16 v[16:31], v[164:167], v[238:241], v[16:31]
	v_max_f32_e32 v164, v81, v81
	v_max_f32_e32 v165, v80, v80
	v_max_f32_e32 v164, v165, v164
	v_max3_f32 v164, v164, v82, v83
	v_max3_f32 v164, v164, v84, v85
	v_max3_f32 v164, v164, v86, v87
	v_max3_f32 v164, v164, v88, v89
	v_max3_f32 v164, v164, v90, v91
	v_max3_f32 v164, v164, v92, v93
	s_waitcnt lgkmcnt(4)
	v_mfma_f32_32x32x16_bf16 v[16:31], v[214:217], v[242:245], v[16:31]
	v_max3_f32 v164, v164, v94, v95
	v_max3_f32 v164, v164, v64, v65
	v_max3_f32 v164, v164, v66, v67
	v_max3_f32 v164, v164, v68, v69
	v_max3_f32 v164, v164, v70, v71
	v_max3_f32 v164, v164, v72, v73
	v_max3_f32 v164, v164, v74, v75
	v_max3_f32 v164, v164, v76, v77
	s_waitcnt lgkmcnt(2)
	v_mfma_f32_32x32x16_bf16 v[16:31], v[222:225], v[246:249], v[16:31]
	v_max3_f32 v164, v164, v78, v79
	v_mov_b32_e32 v165, v164
	s_nop 1
	v_permlane32_swap_b32_e32 v164, v165
	v_max_f32_e32 v165, v165, v165
	v_max_f32_e32 v164, v164, v164
	v_max_f32_e32 v164, v164, v165
	v_sub_f32_e32 v165, v164, v207
	v_cmp_ge_f32_e32 vcc, s46, v165
	v_max_f32_e32 v165, v207, v207
	v_max_f32_e32 v164, v165, v164
	s_waitcnt lgkmcnt(0)
	v_mfma_f32_32x32x16_bf16 v[16:31], v[230:233], v[250:253], v[16:31]
	v_sub_f32_e32 v165, v207, v164
	v_mul_f32_e32 v165, 0x3dd53b94, v165
	v_exp_f32_e32 v165, v165
	s_cmp_eq_u64 vcc, exec
	s_cselect_b64 s[38:39], -1, 0
	s_barrier
	s_waitcnt vmcnt(0)
	v_cndmask_b32_e64 v221, v165, 1.0, s[38:39]
	v_cmp_gt_f32_e32 vcc, 1.0, v221
	s_waitcnt vmcnt(4)
	ds_write_b128 v183, v[144:147]
	s_waitcnt vmcnt(2)
	ds_write_b128 v184, v[156:159]
	ds_write_b128 v185, v[148:151] offset:32768
	s_waitcnt vmcnt(1)
	ds_write_b128 v187, v[152:155] offset:32768
	s_waitcnt vmcnt(0)
	ds_write_b128 v191, v[160:163] offset:32768
	s_cbranch_vccz .LBB0_1139
	s_and_saveexec_b64 s[2:3], s[36:37]
	ds_write_b32 v179, v221 offset:128
	s_or_b64 exec, exec, s[2:3]
	s_waitcnt lgkmcnt(0)
	v_add_u32_e32 v156, s14, v178
	ds_read_b128 v[144:147], v156 offset:224
	ds_read_b128 v[148:151], v156 offset:192
	ds_read_b128 v[152:155], v156 offset:160
	ds_read_b128 v[156:159], v156 offset:128
	s_waitcnt lgkmcnt(3)
	v_pk_mul_f32 v[12:13], v[12:13], v[144:145]
	s_waitcnt lgkmcnt(2)
	v_pk_mul_f32 v[8:9], v[8:9], v[148:149]
	s_waitcnt lgkmcnt(1)
	v_pk_mul_f32 v[4:5], v[4:5], v[152:153]
	v_pk_mul_f32 v[14:15], v[14:15], v[146:147]
	v_pk_mul_f32 v[10:11], v[10:11], v[150:151]
	v_pk_mul_f32 v[6:7], v[6:7], v[154:155]
	s_waitcnt lgkmcnt(0)
	v_pk_mul_f32 v[2:3], v[2:3], v[158:159]
	v_pk_mul_f32 v[0:1], v[0:1], v[156:157]
	v_pk_mul_f32 v[60:61], v[60:61], v[144:145]
	v_pk_mul_f32 v[56:57], v[56:57], v[148:149]
	v_pk_mul_f32 v[52:53], v[52:53], v[152:153]
	v_pk_mul_f32 v[62:63], v[62:63], v[146:147]
	v_pk_mul_f32 v[58:59], v[58:59], v[150:151]
	v_pk_mul_f32 v[54:55], v[54:55], v[154:155]
	v_pk_mul_f32 v[50:51], v[50:51], v[158:159]
	v_pk_mul_f32 v[48:49], v[48:49], v[156:157]
	v_pk_mul_f32 v[44:45], v[44:45], v[144:145]
	v_pk_mul_f32 v[40:41], v[40:41], v[148:149]
	v_pk_mul_f32 v[36:37], v[36:37], v[152:153]
	v_pk_mul_f32 v[46:47], v[46:47], v[146:147]
	v_pk_mul_f32 v[42:43], v[42:43], v[150:151]
	v_pk_mul_f32 v[38:39], v[38:39], v[154:155]
	v_pk_mul_f32 v[34:35], v[34:35], v[158:159]
	v_pk_mul_f32 v[32:33], v[32:33], v[156:157]
	v_pk_mul_f32 v[28:29], v[28:29], v[144:145]
	v_pk_mul_f32 v[24:25], v[24:25], v[148:149]
	v_pk_mul_f32 v[20:21], v[20:21], v[152:153]
	v_pk_mul_f32 v[30:31], v[30:31], v[146:147]
	v_pk_mul_f32 v[26:27], v[26:27], v[150:151]
	v_pk_mul_f32 v[22:23], v[22:23], v[154:155]
	v_pk_mul_f32 v[18:19], v[18:19], v[158:159]
	v_pk_mul_f32 v[16:17], v[16:17], v[156:157]
.LBB0_1139:
	v_cndmask_b32_e64 v207, v164, v207, s[38:39]
	v_mul_f32_e32 v160, 0xbdd53b94, v207
	v_fmamk_f32 v80, v80, 0x3dd53b94, v160
	v_fmamk_f32 v81, v81, 0x3dd53b94, v160
	v_fmamk_f32 v82, v82, 0x3dd53b94, v160
	v_fmamk_f32 v83, v83, 0x3dd53b94, v160
	v_fmamk_f32 v84, v84, 0x3dd53b94, v160
	v_fmamk_f32 v85, v85, 0x3dd53b94, v160
	v_fmamk_f32 v86, v86, 0x3dd53b94, v160
	v_fmamk_f32 v87, v87, 0x3dd53b94, v160
	v_fmamk_f32 v88, v88, 0x3dd53b94, v160
	v_fmamk_f32 v89, v89, 0x3dd53b94, v160
	v_fmamk_f32 v90, v90, 0x3dd53b94, v160
	v_fmamk_f32 v91, v91, 0x3dd53b94, v160
	v_fmamk_f32 v92, v92, 0x3dd53b94, v160
	v_fmamk_f32 v93, v93, 0x3dd53b94, v160
	v_fmamk_f32 v94, v94, 0x3dd53b94, v160
	v_fmamk_f32 v95, v95, 0x3dd53b94, v160
	v_fmamk_f32 v227, v68, 0x3dd53b94, v160
	v_fmamk_f32 v164, v71, 0x3dd53b94, v160
	v_fmamk_f32 v165, v72, 0x3dd53b94, v160
	v_fmamk_f32 v238, v77, 0x3dd53b94, v160
	v_fmamk_f32 v223, v64, 0x3dd53b94, v160
	v_fmamk_f32 v224, v65, 0x3dd53b94, v160
	v_fmamk_f32 v225, v66, 0x3dd53b94, v160
	v_fmamk_f32 v226, v67, 0x3dd53b94, v160
	v_fmamk_f32 v162, v69, 0x3dd53b94, v160
	v_fmamk_f32 v163, v70, 0x3dd53b94, v160
	v_fmamk_f32 v166, v73, 0x3dd53b94, v160
	v_fmamk_f32 v167, v74, 0x3dd53b94, v160
	v_fmamk_f32 v222, v75, 0x3dd53b94, v160
	v_fmamk_f32 v161, v76, 0x3dd53b94, v160
	v_exp_f32_e32 v157, v80
	v_exp_f32_e32 v159, v81
	v_exp_f32_e32 v155, v82
	v_exp_f32_e32 v158, v83
	v_exp_f32_e32 v154, v84
	v_exp_f32_e32 v156, v85
	v_exp_f32_e32 v152, v86
	v_exp_f32_e32 v153, v87
	v_exp_f32_e32 v149, v88
	v_exp_f32_e32 v151, v89
	v_exp_f32_e32 v148, v90
	v_exp_f32_e32 v150, v91
	v_exp_f32_e32 v145, v92
	v_exp_f32_e32 v147, v93
	v_exp_f32_e32 v144, v94
	v_exp_f32_e32 v146, v95
	v_fmamk_f32 v239, v78, 0x3dd53b94, v160
	v_fmac_f32_e32 v160, 0x3dd53b94, v79
	s_waitcnt lgkmcnt(0)
	s_barrier
	ds_read_b128 v[64:67], v194 offset:32768
	ds_read_b128 v[68:71], v194 offset:45056
	ds_read_b128 v[214:217], v197 offset:32768
	ds_read_b128 v[230:233], v197 offset:45056
	v_exp_f32_e32 v223, v223
	v_exp_f32_e32 v224, v224
	s_waitcnt lgkmcnt(3)
	v_mfma_f32_32x32x16_bf16 v[80:95], v[64:67], v[140:143], 0
	v_exp_f32_e32 v225, v225
	v_exp_f32_e32 v226, v226
	v_exp_f32_e32 v162, v162
	v_exp_f32_e32 v163, v163
	v_exp_f32_e32 v234, v167
	v_exp_f32_e32 v235, v222
	v_exp_f32_e32 v161, v161
	s_waitcnt lgkmcnt(2)
	v_mfma_f32_32x32x16_bf16 v[64:79], v[68:71], v[140:143], 0
	v_exp_f32_e32 v240, v238
	v_exp_f32_e32 v239, v239
	v_exp_f32_e32 v160, v160
	s_waitcnt lgkmcnt(0)
	v_mfma_f32_32x32x16_bf16 v[64:79], v[230:233], v[136:139], v[64:79]
	v_mfma_f32_32x32x16_bf16 v[80:95], v[214:217], v[136:139], v[80:95]
	ds_read_b128 v[214:217], v196 offset:32768
	ds_read_b128 v[230:233], v196 offset:45056
	s_waitcnt lgkmcnt(0)
	v_mfma_f32_32x32x16_bf16 v[64:79], v[230:233], v[132:135], v[64:79]
	v_mfma_f32_32x32x16_bf16 v[80:95], v[214:217], v[132:135], v[80:95]
	ds_read_b128 v[214:217], v195 offset:32768
	ds_read_b128 v[230:233], v195 offset:45056
	s_waitcnt lgkmcnt(0)
	v_mfma_f32_32x32x16_bf16 v[64:79], v[230:233], v[128:131], v[64:79]
	v_mfma_f32_32x32x16_bf16 v[80:95], v[214:217], v[128:131], v[80:95]
	ds_read_b128 v[214:217], v193 offset:32768
	ds_read_b128 v[230:233], v193 offset:45056
	s_waitcnt lgkmcnt(0)
	v_mfma_f32_32x32x16_bf16 v[64:79], v[230:233], v[124:127], v[64:79]
	v_mfma_f32_32x32x16_bf16 v[80:95], v[214:217], v[124:127], v[80:95]
	ds_read_b128 v[214:217], v192 offset:32768
	ds_read_b128 v[230:233], v192 offset:45056
	s_waitcnt lgkmcnt(0)
	v_mfma_f32_32x32x16_bf16 v[64:79], v[230:233], v[120:123], v[64:79]
	v_mfma_f32_32x32x16_bf16 v[80:95], v[214:217], v[120:123], v[80:95]
	ds_read_b128 v[214:217], v186 offset:32768
	ds_read_b128 v[230:233], v186 offset:45056
	s_waitcnt lgkmcnt(0)
	v_mfma_f32_32x32x16_bf16 v[64:79], v[230:233], v[116:119], v[64:79]
	v_mfma_f32_32x32x16_bf16 v[80:95], v[214:217], v[116:119], v[80:95]
	ds_read_b128 v[214:217], v189 offset:32768
	ds_read_b128 v[230:233], v189 offset:45056
	s_waitcnt lgkmcnt(0)
	v_mfma_f32_32x32x16_bf16 v[64:79], v[230:233], v[112:115], v[64:79]
	v_mfma_f32_32x32x16_bf16 v[80:95], v[214:217], v[112:115], v[80:95]
	ds_read_b128 v[214:217], v190 offset:32768
	ds_read_b128 v[230:233], v190 offset:45056
	s_waitcnt lgkmcnt(0)
	v_mfma_f32_32x32x16_bf16 v[64:79], v[230:233], v[108:111], v[64:79]
	v_mfma_f32_32x32x16_bf16 v[80:95], v[214:217], v[108:111], v[80:95]
	ds_read_b128 v[214:217], v188 offset:32768
	ds_read_b128 v[230:233], v188 offset:45056
	s_waitcnt lgkmcnt(0)
	v_mfma_f32_32x32x16_bf16 v[64:79], v[230:233], v[104:107], v[64:79]
	v_mfma_f32_32x32x16_bf16 v[80:95], v[214:217], v[104:107], v[80:95]
	ds_read_b128 v[214:217], v199 offset:32768
	ds_read_b128 v[230:233], v199 offset:45056
	s_waitcnt lgkmcnt(0)
	v_mfma_f32_32x32x16_bf16 v[64:79], v[230:233], v[100:103], v[64:79]
	v_mfma_f32_32x32x16_bf16 v[80:95], v[214:217], v[100:103], v[80:95]
	ds_read_b128 v[214:217], v198 offset:32768
	ds_read_b128 v[230:233], v198 offset:45056
	s_waitcnt lgkmcnt(0)
	v_mfma_f32_32x32x16_bf16 v[64:79], v[230:233], v[96:99], v[64:79]
	v_exp_f32_e32 v231, v164
	v_add_f32_e32 v164, 0, v157
	v_add_f32_e32 v164, v159, v164
	v_add_f32_e32 v164, v155, v164
	v_add_f32_e32 v164, v158, v164
	v_add_f32_e32 v164, v154, v164
	v_add_f32_e32 v164, v156, v164
	v_add_f32_e32 v164, v152, v164
	v_add_f32_e32 v164, v153, v164
	v_add_f32_e32 v164, v149, v164
	v_add_f32_e32 v164, v151, v164
	v_add_f32_e32 v164, v148, v164
	v_add_f32_e32 v164, v150, v164
	v_add_f32_e32 v164, v145, v164
	v_add_f32_e32 v164, v147, v164
	v_add_f32_e32 v164, v144, v164
	v_add_f32_e32 v164, v146, v164
	v_exp_f32_e32 v230, v227
	v_add_f32_e32 v164, v223, v164
	v_add_f32_e32 v164, v224, v164
	v_add_f32_e32 v164, v225, v164
	v_add_f32_e32 v164, v226, v164
	v_exp_f32_e32 v232, v165
	v_add_f32_e32 v164, v230, v164
	v_exp_f32_e32 v233, v166
	v_add_f32_e32 v164, v162, v164
	v_add_f32_e32 v164, v163, v164
	v_add_f32_e32 v164, v231, v164
	v_add_f32_e32 v164, v232, v164
	v_add_f32_e32 v164, v233, v164
	v_mfma_f32_32x32x16_bf16 v[80:95], v[214:217], v[96:99], v[80:95]
	v_add_f32_e32 v164, v234, v164
	v_add_f32_e32 v164, v235, v164
	v_add_f32_e32 v164, v161, v164
	v_add_f32_e32 v164, v240, v164
	v_add_f32_e32 v164, v239, v164
	v_add_f32_e32 v227, v160, v164
	v_mov_b32_e32 v238, v227
	v_cvt_pk_bf16_f32 v164, v157, v159
	v_cvt_pk_bf16_f32 v165, v155, v158
	v_cvt_pk_bf16_f32 v166, v154, v156
	v_cvt_pk_bf16_f32 v167, v152, v153
	s_nop 1
	v_permlane32_swap_b32_e32 v227, v238
	v_permlane32_swap_b32_e32 v164, v166
	v_permlane32_swap_b32_e32 v165, v167
	v_cvt_pk_bf16_f32 v214, v149, v151
	v_cvt_pk_bf16_f32 v215, v148, v150
	v_cvt_pk_bf16_f32 v216, v145, v147
	v_cvt_pk_bf16_f32 v217, v144, v146
	v_cvt_pk_bf16_f32 v222, v223, v224
	v_cvt_pk_bf16_f32 v223, v225, v226
	v_cvt_pk_bf16_f32 v224, v230, v162
	v_cvt_pk_bf16_f32 v225, v163, v231
	v_cvt_pk_bf16_f32 v230, v232, v233
	v_cvt_pk_bf16_f32 v231, v234, v235
	v_cvt_pk_bf16_f32 v232, v161, v240
	v_cvt_pk_bf16_f32 v233, v239, v160
	s_nop 0
	v_permlane32_swap_b32_e32 v214, v216
	v_permlane32_swap_b32_e32 v215, v217
	v_permlane32_swap_b32_e32 v222, v224
	v_permlane32_swap_b32_e32 v223, v225
	v_permlane32_swap_b32_e32 v230, v232
	v_permlane32_swap_b32_e32 v231, v233
	s_mov_b32 s2, 0x4bfc0000
	v_add_co_u32_e32 v148, vcc, s2, v172
	s_mov_b32 s2, 0x4bfe0000
	s_nop 0
	v_addc_co_u32_e32 v149, vcc, 0, v173, vcc
	v_add_co_u32_e32 v152, vcc, s2, v172
	s_mov_b32 s2, 0x45406000
	s_nop 0
	v_addc_co_u32_e32 v153, vcc, 0, v173, vcc
	global_load_dwordx4 v[144:147], v[148:149], off offset:256
	s_nop 0
	global_load_dwordx4 v[148:151], v[148:149], off
	s_nop 0
	global_load_dwordx4 v[156:159], v[152:153], off offset:256
	s_nop 0
	global_load_dwordx4 v[152:155], v[152:153], off
	v_add_co_u32_e32 v160, vcc, s2, v174
	s_nop 1
	v_addc_co_u32_e32 v161, vcc, 0, v175, vcc
	global_load_dwordx4 v[160:163], v[160:161], off
	ds_read_b64_tr_b16 v[172:173], v181 offset:0
	ds_read_b64_tr_b16 v[174:175], v181 offset:0x800
	ds_read_b64_tr_b16 v[240:241], v181 offset:0x1000
	ds_read_b64_tr_b16 v[242:243], v181 offset:0x1800
	ds_read_b64_tr_b16 v[244:245], v181 offset:0x2000
	ds_read_b64_tr_b16 v[246:247], v181 offset:0x2800
	ds_read_b64_tr_b16 v[248:249], v181 offset:0x3000
	ds_read_b64_tr_b16 v[250:251], v181 offset:0x3800
	s_waitcnt lgkmcnt(6)
	s_nop 0
	v_mfma_f32_32x32x16_bf16 v[0:15], v[164:167], v[172:175], v[0:15]
	ds_read_b64_tr_b16 v[172:173], v181 offset:0x200
	ds_read_b64_tr_b16 v[174:175], v181 offset:0xa00
	s_waitcnt lgkmcnt(6)
	v_mfma_f32_32x32x16_bf16 v[0:15], v[214:217], v[240:243], v[0:15]
	ds_read_b64_tr_b16 v[240:241], v181 offset:0x1200
	ds_read_b64_tr_b16 v[242:243], v181 offset:0x1a00
	s_waitcnt lgkmcnt(6)
	v_mfma_f32_32x32x16_bf16 v[0:15], v[222:225], v[244:247], v[0:15]
	ds_read_b64_tr_b16 v[244:245], v181 offset:0x2200
	ds_read_b64_tr_b16 v[246:247], v181 offset:0x2a00
	s_waitcnt lgkmcnt(6)
	v_mfma_f32_32x32x16_bf16 v[0:15], v[230:233], v[248:251], v[0:15]
	ds_read_b64_tr_b16 v[248:249], v181 offset:0x3200
	ds_read_b64_tr_b16 v[250:251], v181 offset:0x3a00
	s_waitcnt lgkmcnt(6)
	v_mfma_f32_32x32x16_bf16 v[48:63], v[164:167], v[172:175], v[48:63]
	ds_read_b64_tr_b16 v[172:173], v181 offset:0x400
	ds_read_b64_tr_b16 v[174:175], v181 offset:0xc00
	s_waitcnt lgkmcnt(6)
	v_mfma_f32_32x32x16_bf16 v[48:63], v[214:217], v[240:243], v[48:63]
	ds_read_b64_tr_b16 v[240:241], v181 offset:0x1400
	ds_read_b64_tr_b16 v[242:243], v181 offset:0x1c00
	s_waitcnt lgkmcnt(6)
	v_mfma_f32_32x32x16_bf16 v[48:63], v[222:225], v[244:247], v[48:63]
	ds_read_b64_tr_b16 v[244:245], v181 offset:0x2400
	ds_read_b64_tr_b16 v[246:247], v181 offset:0x2c00
	s_waitcnt lgkmcnt(6)
	v_mfma_f32_32x32x16_bf16 v[48:63], v[230:233], v[248:251], v[48:63]
	ds_read_b64_tr_b16 v[248:249], v181 offset:0x3400
	ds_read_b64_tr_b16 v[250:251], v181 offset:0x3c00
	s_waitcnt lgkmcnt(6)
	v_mfma_f32_32x32x16_bf16 v[32:47], v[164:167], v[172:175], v[32:47]
	ds_read_b64_tr_b16 v[172:173], v181 offset:0x600
	ds_read_b64_tr_b16 v[174:175], v181 offset:0xe00
	s_waitcnt lgkmcnt(6)
	v_mfma_f32_32x32x16_bf16 v[32:47], v[214:217], v[240:243], v[32:47]
	ds_read_b64_tr_b16 v[240:241], v181 offset:0x1600
	ds_read_b64_tr_b16 v[242:243], v181 offset:0x1e00
	s_waitcnt lgkmcnt(6)
	v_mfma_f32_32x32x16_bf16 v[32:47], v[222:225], v[244:247], v[32:47]
	ds_read_b64_tr_b16 v[244:245], v181 offset:0x2600
	ds_read_b64_tr_b16 v[246:247], v181 offset:0x2e00
	s_waitcnt lgkmcnt(6)
	v_mfma_f32_32x32x16_bf16 v[32:47], v[230:233], v[248:251], v[32:47]
	ds_read_b64_tr_b16 v[248:249], v181 offset:0x3600
	ds_read_b64_tr_b16 v[250:251], v181 offset:0x3e00
	s_waitcnt lgkmcnt(6)
	v_mfma_f32_32x32x16_bf16 v[16:31], v[164:167], v[172:175], v[16:31]
	v_max_f32_e32 v164, v81, v81
	v_max_f32_e32 v165, v80, v80
	v_max_f32_e32 v164, v165, v164
	v_max3_f32 v164, v164, v82, v83
	v_max3_f32 v164, v164, v84, v85
	v_max3_f32 v164, v164, v86, v87
	v_max3_f32 v164, v164, v88, v89
	v_max3_f32 v164, v164, v90, v91
	v_max3_f32 v164, v164, v92, v93
	s_waitcnt lgkmcnt(4)
	v_mfma_f32_32x32x16_bf16 v[16:31], v[214:217], v[240:243], v[16:31]
	v_max3_f32 v164, v164, v94, v95
	v_max3_f32 v164, v164, v64, v65
	v_max3_f32 v164, v164, v66, v67
	v_max3_f32 v164, v164, v68, v69
	v_max3_f32 v164, v164, v70, v71
	v_max3_f32 v164, v164, v72, v73
	v_max3_f32 v164, v164, v74, v75
	v_max3_f32 v164, v164, v76, v77
	s_waitcnt lgkmcnt(2)
	v_mfma_f32_32x32x16_bf16 v[16:31], v[222:225], v[244:247], v[16:31]
	v_max3_f32 v164, v164, v78, v79
	v_mov_b32_e32 v165, v164
	s_nop 1
	v_permlane32_swap_b32_e32 v164, v165
	v_max_f32_e32 v165, v165, v165
	v_max_f32_e32 v164, v164, v164
	v_max_f32_e32 v164, v164, v165
	v_sub_f32_e32 v165, v164, v207
	v_cmp_ge_f32_e32 vcc, s46, v165
	v_max_f32_e32 v165, v207, v207
	v_max_f32_e32 v165, v165, v164
	s_waitcnt lgkmcnt(0)
	v_mfma_f32_32x32x16_bf16 v[16:31], v[230:233], v[248:251], v[16:31]
	v_sub_f32_e32 v164, v207, v165
	v_mul_f32_e32 v164, 0x3dd53b94, v164
	v_exp_f32_e32 v164, v164
	s_cmp_eq_u64 vcc, exec
	s_cselect_b64 s[38:39], -1, 0
	s_barrier
	s_waitcnt vmcnt(0)
	v_cndmask_b32_e64 v164, v164, 1.0, s[38:39]
	v_cmp_gt_f32_e32 vcc, 1.0, v164
	s_waitcnt vmcnt(4)
	ds_write_b128 v183, v[144:147] offset:16384
	s_waitcnt vmcnt(2)
	ds_write_b128 v184, v[156:159] offset:16384
	ds_write_b128 v185, v[148:151] offset:57344
	s_waitcnt vmcnt(1)
	ds_write_b128 v187, v[152:155] offset:57344
	s_waitcnt vmcnt(0)
	ds_write_b128 v191, v[160:163] offset:57344
	s_cbranch_vccz .LBB0_1143
	s_and_saveexec_b64 s[2:3], s[36:37]
	ds_write_b32 v179, v164 offset:128
	s_or_b64 exec, exec, s[2:3]
	s_waitcnt lgkmcnt(0)
	v_add_u32_e32 v156, s14, v178
	ds_read_b128 v[144:147], v156 offset:224
	ds_read_b128 v[148:151], v156 offset:192
	ds_read_b128 v[152:155], v156 offset:160
	ds_read_b128 v[156:159], v156 offset:128
	s_waitcnt lgkmcnt(3)
	v_pk_mul_f32 v[12:13], v[12:13], v[144:145]
	s_waitcnt lgkmcnt(2)
	v_pk_mul_f32 v[8:9], v[8:9], v[148:149]
	s_waitcnt lgkmcnt(1)
	v_pk_mul_f32 v[4:5], v[4:5], v[152:153]
	v_pk_mul_f32 v[14:15], v[14:15], v[146:147]
	v_pk_mul_f32 v[10:11], v[10:11], v[150:151]
	v_pk_mul_f32 v[6:7], v[6:7], v[154:155]
	s_waitcnt lgkmcnt(0)
	v_pk_mul_f32 v[2:3], v[2:3], v[158:159]
	v_pk_mul_f32 v[0:1], v[0:1], v[156:157]
	v_pk_mul_f32 v[60:61], v[60:61], v[144:145]
	v_pk_mul_f32 v[56:57], v[56:57], v[148:149]
	v_pk_mul_f32 v[52:53], v[52:53], v[152:153]
	v_pk_mul_f32 v[62:63], v[62:63], v[146:147]
	v_pk_mul_f32 v[58:59], v[58:59], v[150:151]
	v_pk_mul_f32 v[54:55], v[54:55], v[154:155]
	v_pk_mul_f32 v[50:51], v[50:51], v[158:159]
	v_pk_mul_f32 v[48:49], v[48:49], v[156:157]
	v_pk_mul_f32 v[44:45], v[44:45], v[144:145]
	v_pk_mul_f32 v[40:41], v[40:41], v[148:149]
	v_pk_mul_f32 v[36:37], v[36:37], v[152:153]
	v_pk_mul_f32 v[46:47], v[46:47], v[146:147]
	v_pk_mul_f32 v[42:43], v[42:43], v[150:151]
	v_pk_mul_f32 v[38:39], v[38:39], v[154:155]
	v_pk_mul_f32 v[34:35], v[34:35], v[158:159]
	v_pk_mul_f32 v[32:33], v[32:33], v[156:157]
	v_pk_mul_f32 v[28:29], v[28:29], v[144:145]
	v_pk_mul_f32 v[24:25], v[24:25], v[148:149]
	v_pk_mul_f32 v[20:21], v[20:21], v[152:153]
	v_pk_mul_f32 v[30:31], v[30:31], v[146:147]
	v_pk_mul_f32 v[26:27], v[26:27], v[150:151]
	v_pk_mul_f32 v[22:23], v[22:23], v[154:155]
	v_pk_mul_f32 v[18:19], v[18:19], v[158:159]
	v_pk_mul_f32 v[16:17], v[16:17], v[156:157]

.LBB0_1145:
	ds_read_b128 v[64:67], v194 offset:57344
	ds_read_b128 v[68:71], v212 offset:57344
	s_waitcnt lgkmcnt(1)
	v_mfma_f32_32x32x16_bf16 v[80:95], v[64:67], v[140:143], 0
	s_waitcnt lgkmcnt(0)
	v_mfma_f32_32x32x16_bf16 v[64:79], v[68:71], v[140:143], 0
	ds_read_b128 v[140:143], v197 offset:57344
	ds_read_b128 v[168:171], v211 offset:57344
	s_waitcnt lgkmcnt(1)
	v_mfma_f32_32x32x16_bf16 v[80:95], v[140:143], v[136:139], v[80:95]
	s_waitcnt lgkmcnt(0)
	v_mfma_f32_32x32x16_bf16 v[64:79], v[168:171], v[136:139], v[64:79]
	ds_read_b128 v[136:139], v196 offset:57344
	ds_read_b128 v[140:143], v210 offset:57344
	s_waitcnt lgkmcnt(1)
	v_mfma_f32_32x32x16_bf16 v[80:95], v[136:139], v[132:135], v[80:95]
	s_waitcnt lgkmcnt(0)
	v_mfma_f32_32x32x16_bf16 v[64:79], v[140:143], v[132:135], v[64:79]
	ds_read_b128 v[132:135], v195 offset:57344
	ds_read_b128 v[136:139], v209 offset:57344
	s_waitcnt lgkmcnt(1)
	v_mfma_f32_32x32x16_bf16 v[80:95], v[132:135], v[128:131], v[80:95]
	s_waitcnt lgkmcnt(0)
	v_mfma_f32_32x32x16_bf16 v[64:79], v[136:139], v[128:131], v[64:79]
	ds_read_b128 v[128:131], v193 offset:57344
	ds_read_b128 v[132:135], v208 offset:57344
	s_waitcnt lgkmcnt(1)
	v_mfma_f32_32x32x16_bf16 v[80:95], v[128:131], v[124:127], v[80:95]
	s_waitcnt lgkmcnt(0)
	v_mfma_f32_32x32x16_bf16 v[64:79], v[132:135], v[124:127], v[64:79]
	ds_read_b128 v[124:127], v192 offset:57344
	ds_read_b128 v[128:131], v206 offset:57344
	s_waitcnt lgkmcnt(1)
	v_mfma_f32_32x32x16_bf16 v[80:95], v[124:127], v[120:123], v[80:95]
	s_waitcnt lgkmcnt(0)
	v_mfma_f32_32x32x16_bf16 v[64:79], v[128:131], v[120:123], v[64:79]
	ds_read_b128 v[120:123], v186 offset:57344
	ds_read_b128 v[124:127], v205 offset:57344
	s_waitcnt lgkmcnt(1)
	v_mfma_f32_32x32x16_bf16 v[80:95], v[120:123], v[116:119], v[80:95]
	s_waitcnt lgkmcnt(0)
	v_mfma_f32_32x32x16_bf16 v[64:79], v[124:127], v[116:119], v[64:79]
	ds_read_b128 v[116:119], v189 offset:57344
	ds_read_b128 v[120:123], v204 offset:57344
	s_waitcnt lgkmcnt(1)
	v_mfma_f32_32x32x16_bf16 v[80:95], v[116:119], v[112:115], v[80:95]
	s_waitcnt lgkmcnt(0)
	v_mfma_f32_32x32x16_bf16 v[64:79], v[120:123], v[112:115], v[64:79]
	ds_read_b128 v[112:115], v190 offset:57344
	ds_read_b128 v[116:119], v203 offset:57344
	v_exp_f32_e32 v120, v144
	v_exp_f32_e32 v121, v145
	s_waitcnt lgkmcnt(1)
	v_mfma_f32_32x32x16_bf16 v[80:95], v[112:115], v[108:111], v[80:95]
	s_waitcnt lgkmcnt(0)
	v_mfma_f32_32x32x16_bf16 v[64:79], v[116:119], v[108:111], v[64:79]
	ds_read_b128 v[108:111], v188 offset:57344
	ds_read_b128 v[112:115], v202 offset:57344
	v_exp_f32_e32 v116, v154
	v_exp_f32_e32 v117, v155
	v_exp_f32_e32 v118, v150
	v_exp_f32_e32 v119, v151
	s_waitcnt lgkmcnt(1)
	v_mfma_f32_32x32x16_bf16 v[80:95], v[108:111], v[104:107], v[80:95]
	s_waitcnt lgkmcnt(0)
	v_mfma_f32_32x32x16_bf16 v[64:79], v[112:115], v[104:107], v[64:79]
	ds_read_b128 v[104:107], v199 offset:57344
	ds_read_b128 v[108:111], v201 offset:57344
	v_exp_f32_e32 v112, v148
	v_exp_f32_e32 v113, v149
	v_exp_f32_e32 v114, v146
	v_exp_f32_e32 v115, v147
	s_waitcnt lgkmcnt(1)
	v_mfma_f32_32x32x16_bf16 v[80:95], v[104:107], v[100:103], v[80:95]
	s_waitcnt lgkmcnt(0)
	v_mfma_f32_32x32x16_bf16 v[64:79], v[108:111], v[100:103], v[64:79]
	ds_read_b128 v[100:103], v198 offset:57344
	ds_read_b128 v[104:107], v200 offset:57344
	v_exp_f32_e32 v108, v156
	v_exp_f32_e32 v109, v157
	v_exp_f32_e32 v110, v152
	v_exp_f32_e32 v111, v153
	s_waitcnt lgkmcnt(1)
	v_mfma_f32_32x32x16_bf16 v[80:95], v[100:103], v[96:99], v[80:95]
	s_waitcnt lgkmcnt(0)
	v_mfma_f32_32x32x16_bf16 v[64:79], v[104:107], v[96:99], v[64:79]
	v_add_f32_e32 v96, 0, v165
	v_add_f32_e32 v96, v224, v96
	v_add_f32_e32 v96, v166, v96
	v_add_f32_e32 v96, v225, v96
	v_add_f32_e32 v96, v223, v96
	v_add_f32_e32 v96, v226, v96
	v_add_f32_e32 v96, v167, v96
	v_add_f32_e32 v96, v222, v96
	v_add_f32_e32 v96, v172, v96
	v_add_f32_e32 v96, v174, v96
	v_add_f32_e32 v96, v173, v96
	v_add_f32_e32 v96, v175, v96
	v_exp_f32_e32 v106, v158
	v_add_f32_e32 v96, v160, v96
	v_exp_f32_e32 v107, v159
	v_add_f32_e32 v96, v162, v96
	v_add_f32_e32 v96, v161, v96
	v_add_f32_e32 v96, v163, v96
	v_add_f32_e32 v96, v106, v96
	v_add_f32_e32 v96, v107, v96
	v_add_f32_e32 v96, v108, v96
	v_add_f32_e32 v96, v109, v96
	v_add_f32_e32 v96, v110, v96
	v_add_f32_e32 v96, v111, v96
	v_add_f32_e32 v96, v112, v96
	v_add_f32_e32 v96, v113, v96
	v_add_f32_e32 v96, v114, v96
	v_add_f32_e32 v96, v115, v96
	v_add_f32_e32 v96, v116, v96
	v_add_f32_e32 v96, v117, v96
	v_add_f32_e32 v96, v118, v96
	v_add_f32_e32 v96, v119, v96
	v_add_f32_e32 v96, v120, v96
	v_add_f32_e32 v96, v121, v96
	v_mov_b32_e32 v97, v96
	v_cvt_pk_bf16_f32 v98, v165, v224
	v_cvt_pk_bf16_f32 v99, v166, v225
	v_cvt_pk_bf16_f32 v100, v223, v226
	v_cvt_pk_bf16_f32 v101, v167, v222
	s_nop 1
	v_permlane32_swap_b32_e32 v96, v97
	v_permlane32_swap_b32_e32 v98, v100
	v_permlane32_swap_b32_e32 v99, v101
	v_cvt_pk_bf16_f32 v102, v172, v174
	v_cvt_pk_bf16_f32 v103, v173, v175
	v_cvt_pk_bf16_f32 v104, v160, v162
	v_cvt_pk_bf16_f32 v105, v161, v163
	v_cvt_pk_bf16_f32 v106, v106, v107
	v_cvt_pk_bf16_f32 v107, v108, v109
	v_cvt_pk_bf16_f32 v108, v110, v111
	v_cvt_pk_bf16_f32 v109, v112, v113
	v_cvt_pk_bf16_f32 v110, v114, v115
	v_cvt_pk_bf16_f32 v111, v116, v117
	v_cvt_pk_bf16_f32 v112, v118, v119
	v_cvt_pk_bf16_f32 v113, v120, v121
	s_nop 0
	v_permlane32_swap_b32_e32 v102, v104
	v_permlane32_swap_b32_e32 v103, v105
	v_permlane32_swap_b32_e32 v106, v108
	v_permlane32_swap_b32_e32 v107, v109
	v_permlane32_swap_b32_e32 v110, v112
	v_permlane32_swap_b32_e32 v111, v113
	ds_read_b64_tr_b16 v[114:115], v182 offset:0
	ds_read_b64_tr_b16 v[116:117], v182 offset:0x800
	ds_read_b64_tr_b16 v[118:119], v182 offset:0x1000
	ds_read_b64_tr_b16 v[120:121], v182 offset:0x1800
	ds_read_b64_tr_b16 v[122:123], v182 offset:0x2000
	ds_read_b64_tr_b16 v[124:125], v182 offset:0x2800
	ds_read_b64_tr_b16 v[126:127], v182 offset:0x3000
	ds_read_b64_tr_b16 v[128:129], v182 offset:0x3800
	s_waitcnt lgkmcnt(6)
	s_nop 0
	v_mfma_f32_32x32x16_bf16 v[0:15], v[98:101], v[114:117], v[0:15]
	ds_read_b64_tr_b16 v[114:115], v182 offset:0x200
	ds_read_b64_tr_b16 v[116:117], v182 offset:0xa00
	s_waitcnt lgkmcnt(6)
	v_mfma_f32_32x32x16_bf16 v[0:15], v[102:105], v[118:121], v[0:15]
	ds_read_b64_tr_b16 v[118:119], v182 offset:0x1200
	ds_read_b64_tr_b16 v[120:121], v182 offset:0x1a00
	s_waitcnt lgkmcnt(6)
	v_mfma_f32_32x32x16_bf16 v[0:15], v[106:109], v[122:125], v[0:15]
	ds_read_b64_tr_b16 v[122:123], v182 offset:0x2200
	ds_read_b64_tr_b16 v[124:125], v182 offset:0x2a00
	s_waitcnt lgkmcnt(6)
	v_mfma_f32_32x32x16_bf16 v[0:15], v[110:113], v[126:129], v[0:15]
	ds_read_b64_tr_b16 v[126:127], v182 offset:0x3200
	ds_read_b64_tr_b16 v[128:129], v182 offset:0x3a00
	s_waitcnt lgkmcnt(6)
	v_mfma_f32_32x32x16_bf16 v[48:63], v[98:101], v[114:117], v[48:63]
	ds_read_b64_tr_b16 v[114:115], v182 offset:0x400
	ds_read_b64_tr_b16 v[116:117], v182 offset:0xc00
	s_waitcnt lgkmcnt(6)
	v_mfma_f32_32x32x16_bf16 v[48:63], v[102:105], v[118:121], v[48:63]
	ds_read_b64_tr_b16 v[118:119], v182 offset:0x1400
	ds_read_b64_tr_b16 v[120:121], v182 offset:0x1c00
	s_waitcnt lgkmcnt(6)
	v_mfma_f32_32x32x16_bf16 v[48:63], v[106:109], v[122:125], v[48:63]
	ds_read_b64_tr_b16 v[122:123], v182 offset:0x2400
	ds_read_b64_tr_b16 v[124:125], v182 offset:0x2c00
	s_waitcnt lgkmcnt(6)
	v_mfma_f32_32x32x16_bf16 v[48:63], v[110:113], v[126:129], v[48:63]
	ds_read_b64_tr_b16 v[126:127], v182 offset:0x3400
	ds_read_b64_tr_b16 v[128:129], v182 offset:0x3c00
	s_waitcnt lgkmcnt(6)
	v_mfma_f32_32x32x16_bf16 v[32:47], v[98:101], v[114:117], v[32:47]
	ds_read_b64_tr_b16 v[114:115], v182 offset:0x600
	ds_read_b64_tr_b16 v[116:117], v182 offset:0xe00
	s_waitcnt lgkmcnt(6)
	v_mfma_f32_32x32x16_bf16 v[32:47], v[102:105], v[118:121], v[32:47]
	ds_read_b64_tr_b16 v[118:119], v182 offset:0x1600
	ds_read_b64_tr_b16 v[120:121], v182 offset:0x1e00
	s_waitcnt lgkmcnt(6)
	v_mfma_f32_32x32x16_bf16 v[32:47], v[106:109], v[122:125], v[32:47]
	ds_read_b64_tr_b16 v[122:123], v182 offset:0x2600
	ds_read_b64_tr_b16 v[124:125], v182 offset:0x2e00
	s_waitcnt lgkmcnt(6)
	v_mfma_f32_32x32x16_bf16 v[32:47], v[110:113], v[126:129], v[32:47]
	ds_read_b64_tr_b16 v[126:127], v182 offset:0x3600
	ds_read_b64_tr_b16 v[128:129], v182 offset:0x3e00
	s_waitcnt lgkmcnt(6)
	v_mfma_f32_32x32x16_bf16 v[16:31], v[98:101], v[114:117], v[16:31]
	v_max_f32_e32 v98, v81, v81
	v_max_f32_e32 v99, v80, v80
	v_max_f32_e32 v98, v99, v98
	v_max3_f32 v98, v98, v82, v83
	v_max3_f32 v98, v98, v84, v85
	v_max3_f32 v98, v98, v86, v87
	v_max3_f32 v98, v98, v88, v89
	v_max3_f32 v98, v98, v90, v91
	v_max3_f32 v98, v98, v92, v93
	s_waitcnt lgkmcnt(4)
	v_mfma_f32_32x32x16_bf16 v[16:31], v[102:105], v[118:121], v[16:31]
	v_max3_f32 v98, v98, v94, v95
	v_max3_f32 v98, v98, v64, v65
	v_max3_f32 v98, v98, v66, v67
	v_max3_f32 v98, v98, v68, v69
	v_max3_f32 v98, v98, v70, v71
	v_max3_f32 v98, v98, v72, v73
	v_max3_f32 v98, v98, v74, v75
	v_max3_f32 v98, v98, v76, v77
	s_waitcnt lgkmcnt(2)
	v_mfma_f32_32x32x16_bf16 v[16:31], v[106:109], v[122:125], v[16:31]
	v_max3_f32 v98, v98, v78, v79
	v_mov_b32_e32 v99, v98
	s_nop 1
	v_permlane32_swap_b32_e32 v98, v99
	v_max_f32_e32 v99, v99, v99
	v_max_f32_e32 v98, v98, v98
	v_max_f32_e32 v98, v98, v99
	v_sub_f32_e32 v99, v98, v207
	v_cmp_ge_f32_e32 vcc, s46, v99
	v_max_f32_e32 v99, v207, v207
	v_max_f32_e32 v99, v99, v98
	s_waitcnt lgkmcnt(0)
	v_mfma_f32_32x32x16_bf16 v[16:31], v[110:113], v[126:129], v[16:31]
	v_sub_f32_e32 v98, v207, v99
	v_mul_f32_e32 v98, 0x3dd53b94, v98
	v_exp_f32_e32 v98, v98
	s_cmp_eq_u64 vcc, exec
	s_cselect_b64 s[38:39], -1, 0
	v_cndmask_b32_e64 v98, v98, 1.0, s[38:39]
	v_cmp_gt_f32_e32 vcc, 1.0, v98
	s_barrier
	s_cbranch_vccz .LBB0_1149
	s_and_saveexec_b64 s[2:3], s[36:37]
	ds_write_b32 v179, v98 offset:128
	s_or_b64 exec, exec, s[2:3]
	s_waitcnt lgkmcnt(0)
	v_add_u32_e32 v112, s14, v178
	ds_read_b128 v[100:103], v112 offset:224
	ds_read_b128 v[104:107], v112 offset:192
	ds_read_b128 v[108:111], v112 offset:160
	ds_read_b128 v[112:115], v112 offset:128
	s_waitcnt lgkmcnt(3)
	v_pk_mul_f32 v[12:13], v[12:13], v[100:101]
	s_waitcnt lgkmcnt(2)
	v_pk_mul_f32 v[8:9], v[8:9], v[104:105]
	s_waitcnt lgkmcnt(1)
	v_pk_mul_f32 v[4:5], v[4:5], v[108:109]
	v_pk_mul_f32 v[14:15], v[14:15], v[102:103]
	v_pk_mul_f32 v[10:11], v[10:11], v[106:107]
	v_pk_mul_f32 v[6:7], v[6:7], v[110:111]
	s_waitcnt lgkmcnt(0)
	v_pk_mul_f32 v[2:3], v[2:3], v[114:115]
	v_pk_mul_f32 v[0:1], v[0:1], v[112:113]
	v_pk_mul_f32 v[60:61], v[60:61], v[100:101]
	v_pk_mul_f32 v[56:57], v[56:57], v[104:105]
	v_pk_mul_f32 v[52:53], v[52:53], v[108:109]
	v_pk_mul_f32 v[62:63], v[62:63], v[102:103]
	v_pk_mul_f32 v[58:59], v[58:59], v[106:107]
	v_pk_mul_f32 v[54:55], v[54:55], v[110:111]
	v_pk_mul_f32 v[50:51], v[50:51], v[114:115]
	v_pk_mul_f32 v[48:49], v[48:49], v[112:113]
	v_pk_mul_f32 v[44:45], v[44:45], v[100:101]
	v_pk_mul_f32 v[40:41], v[40:41], v[104:105]
	v_pk_mul_f32 v[36:37], v[36:37], v[108:109]
	v_pk_mul_f32 v[46:47], v[46:47], v[102:103]
	v_pk_mul_f32 v[42:43], v[42:43], v[106:107]
	v_pk_mul_f32 v[38:39], v[38:39], v[110:111]
	v_pk_mul_f32 v[34:35], v[34:35], v[114:115]
	v_pk_mul_f32 v[32:33], v[32:33], v[112:113]
	v_pk_mul_f32 v[28:29], v[28:29], v[100:101]
	v_pk_mul_f32 v[24:25], v[24:25], v[104:105]
	v_pk_mul_f32 v[20:21], v[20:21], v[108:109]
	v_pk_mul_f32 v[30:31], v[30:31], v[102:103]
	v_pk_mul_f32 v[26:27], v[26:27], v[106:107]
	v_pk_mul_f32 v[22:23], v[22:23], v[110:111]
	v_pk_mul_f32 v[18:19], v[18:19], v[114:115]
	v_pk_mul_f32 v[16:17], v[16:17], v[112:113]
